# v34 with 2-pair-deep X prefetch in the lane-permuted residual epilogue (X buffers recycled from spent accumulator quads)
# baseline (speedup 1.0000x reference)
;     __device__ __forceinline__ void operator()(const pg8::f32x4 (&acc)[2][2][4][2], const pg8::Unit& u, int wr, int wc, int fr, int fq) const {
;         const int b = u.pm / 9, j = u.pm - b * 9;
;         float* base = (j == 0) ? xc + (size_t)b * CTX * DM : out + ((size_t)b * SEQ + (size_t)(j - 1) * 256) * DM;
;         const float* g = gate + (size_t)((j == 0) ? 16 : b) * MODW;
;         const int col0 = u.pn * 256 + wc * 32 + 4 * fq;
;         pg8::f32x4 gv[2][2];
; #pragma unroll
;         for (int bj = 0; bj < 2; ++bj)
; #pragma unroll
;             for (int n = 0; n < 2; ++n) gv[bj][n] = *(const pg8::f32x4*)(g + col0 + bj * 128 + n * 16);
; #pragma unroll
;         for (int ai = 0; ai < 2; ++ai)
; #pragma unroll
;             for (int m = 0; m < 4; ++m) {
;                 float* rowp = base + (size_t)(ai * 128 + wr * 64 + m * 16 + fr) * DM + col0;
; #pragma unroll
;                 for (int bj = 0; bj < 2; ++bj)
; #pragma unroll
;                     for (int n = 0; n < 2; ++n) {
;                         pg8::f32x4* p = (pg8::f32x4*)(rowp + bj * 128 + n * 16);
;                         pg8::f32x4 xv = *p; xv = xv + gv[bj][n] * acc[ai][bj][m][n]; *p = xv;
;                     }
.LBB0_854:
	s_lshl_b64 s[12:13], s[54:55], 2
	v_lshl_or_b32 v88, s62, 8, v171
	s_add_u32 s12, s41, s12
	v_ashrrev_i32_e32 v89, 31, v88
	s_addc_u32 s13, s0, s13
	v_lshlrev_b64 v[168:169], 2, v[88:89]
	v_lshl_add_u64 v[88:89], s[12:13], 0, v[168:169]
	v_lshl_add_u64 v[168:169], s[50:51], 0, v[168:169]
	v_lshl_add_u64 v[178:179], v[168:169], 0, v[148:149]
	global_load_dwordx4 v[108:111], v[88:89], off
	global_load_dwordx4 v[104:107], v[88:89], off offset:64
	global_load_dwordx4 v[100:103], v[88:89], off offset:512
	s_nop 0
	global_load_dwordx4 v[88:91], v[88:89], off offset:576
	s_mov_b64 s[50:51], -1
	s_andn2_b64 vcc, exec, s[38:39]
	s_waitcnt vmcnt(0)
	v_and_b32_e32 v228, 63, v200
	v_lshrrev_b32_e32 v229, 3, v228
	v_and_b32_e32 v184, 3, v228
	v_lshl_or_b32 v184, v184, 4, v229
	v_lshlrev_b32_e32 v184, 2, v184
	v_add_u32_e32 v185, 32, v184
	v_bfe_u32 v229, v228, 2, 1
	v_lshlrev_b32_e32 v186, 6, v229
	v_mov_b32_e32 v187, 0
	v_sub_u32_e32 v188, 0, v229
	ds_bpermute_b32 v228, v184, v108
	ds_bpermute_b32 v229, v184, v104
	s_waitcnt lgkmcnt(0)
	v_bfi_b32 v190, v188, v229, v228
	ds_bpermute_b32 v228, v184, v109
	ds_bpermute_b32 v229, v184, v105
	s_waitcnt lgkmcnt(0)
	v_bfi_b32 v191, v188, v229, v228
	ds_bpermute_b32 v228, v184, v110
	ds_bpermute_b32 v229, v184, v106
	s_waitcnt lgkmcnt(0)
	v_bfi_b32 v192, v188, v229, v228
	ds_bpermute_b32 v228, v184, v111
	ds_bpermute_b32 v229, v184, v107
	s_waitcnt lgkmcnt(0)
	v_bfi_b32 v193, v188, v229, v228
	ds_bpermute_b32 v228, v184, v100
	ds_bpermute_b32 v229, v184, v88
	s_waitcnt lgkmcnt(0)
	v_bfi_b32 v194, v188, v229, v228
	ds_bpermute_b32 v228, v184, v101
	ds_bpermute_b32 v229, v184, v89
	s_waitcnt lgkmcnt(0)
	v_bfi_b32 v195, v188, v229, v228
	ds_bpermute_b32 v228, v184, v102
	ds_bpermute_b32 v229, v184, v90
	s_waitcnt lgkmcnt(0)
	v_bfi_b32 v196, v188, v229, v228
	ds_bpermute_b32 v228, v184, v103
	ds_bpermute_b32 v229, v184, v91
	s_waitcnt lgkmcnt(0)
	v_bfi_b32 v197, v188, v229, v228
	v_lshl_add_u64 v[178:179], v[168:169], 0, v[148:149]
	ds_bpermute_b32 v174, v184, v178
	ds_bpermute_b32 v175, v184, v179
	ds_bpermute_b32 v176, v185, v178
	ds_bpermute_b32 v177, v185, v179
	s_waitcnt lgkmcnt(0)
	v_lshl_add_u64 v[174:175], v[174:175], 0, v[186:187]
	v_lshl_add_u64 v[176:177], v[176:177], 0, v[186:187]
	global_load_dwordx4 v[204:207], v[174:175], off
	global_load_dwordx4 v[208:211], v[176:177], off
	global_load_dwordx4 v[212:215], v[174:175], off offset:512
	global_load_dwordx4 v[216:219], v[176:177], off offset:512
	ds_bpermute_b32 v228, v184, v142
	ds_bpermute_b32 v229, v184, v138
	ds_bpermute_b32 v230, v184, v143
	ds_bpermute_b32 v231, v184, v139
	s_waitcnt lgkmcnt(0)
	v_bfi_b32 v220, v188, v229, v228
	v_bfi_b32 v221, v188, v231, v230
	ds_bpermute_b32 v228, v184, v144
	ds_bpermute_b32 v229, v184, v140
	ds_bpermute_b32 v230, v184, v145
	ds_bpermute_b32 v231, v184, v141
	s_waitcnt lgkmcnt(0)
	v_bfi_b32 v222, v188, v229, v228
	v_bfi_b32 v223, v188, v231, v230
	ds_bpermute_b32 v228, v185, v142
	ds_bpermute_b32 v229, v185, v138
	ds_bpermute_b32 v230, v185, v143
	ds_bpermute_b32 v231, v185, v139
	s_waitcnt lgkmcnt(0)
	v_bfi_b32 v224, v188, v229, v228
	v_bfi_b32 v225, v188, v231, v230
	ds_bpermute_b32 v228, v185, v144
	ds_bpermute_b32 v229, v185, v140
	ds_bpermute_b32 v230, v185, v145
	ds_bpermute_b32 v231, v185, v141
	s_waitcnt lgkmcnt(0)
	v_bfi_b32 v226, v188, v229, v228
	v_bfi_b32 v227, v188, v231, v230
	v_lshl_add_u64 v[178:179], v[168:169], 0, v[150:151]
	ds_bpermute_b32 v180, v184, v178
	ds_bpermute_b32 v181, v184, v179
	ds_bpermute_b32 v198, v185, v178
	ds_bpermute_b32 v199, v185, v179
	s_waitcnt lgkmcnt(0)
	v_lshl_add_u64 v[180:181], v[180:181], 0, v[186:187]
	v_lshl_add_u64 v[198:199], v[198:199], 0, v[186:187]
	global_load_dwordx4 v[142:145], v[180:181], off
	global_load_dwordx4 v[138:141], v[198:199], off
	s_waitcnt vmcnt(4)
	v_pk_fma_f32 v[206:207], v[222:223], v[192:193], v[206:207]
	v_pk_fma_f32 v[204:205], v[220:221], v[190:191], v[204:205]
	v_pk_fma_f32 v[210:211], v[226:227], v[192:193], v[210:211]
	v_pk_fma_f32 v[208:209], v[224:225], v[190:191], v[208:209]
	global_store_dwordx4 v[174:175], v[204:207], off
	global_store_dwordx4 v[176:177], v[208:211], off
	ds_bpermute_b32 v228, v184, v134
	ds_bpermute_b32 v229, v184, v124
	ds_bpermute_b32 v230, v184, v135
	ds_bpermute_b32 v231, v184, v125
	s_waitcnt lgkmcnt(0)
	v_bfi_b32 v220, v188, v229, v228
	v_bfi_b32 v221, v188, v231, v230
	ds_bpermute_b32 v228, v184, v136
	ds_bpermute_b32 v229, v184, v126
	ds_bpermute_b32 v230, v184, v137
	ds_bpermute_b32 v231, v184, v127
	s_waitcnt lgkmcnt(0)
	v_bfi_b32 v222, v188, v229, v228
	v_bfi_b32 v223, v188, v231, v230
	ds_bpermute_b32 v228, v185, v134
	ds_bpermute_b32 v229, v185, v124
	ds_bpermute_b32 v230, v185, v135
	ds_bpermute_b32 v231, v185, v125
	s_waitcnt lgkmcnt(0)
	v_bfi_b32 v224, v188, v229, v228
	v_bfi_b32 v225, v188, v231, v230
	ds_bpermute_b32 v228, v185, v136
	ds_bpermute_b32 v229, v185, v126
	ds_bpermute_b32 v230, v185, v137
	ds_bpermute_b32 v231, v185, v127
	s_waitcnt lgkmcnt(0)
	v_bfi_b32 v226, v188, v229, v228
	v_bfi_b32 v227, v188, v231, v230
	global_load_dwordx4 v[134:137], v[180:181], off offset:512
	global_load_dwordx4 v[124:127], v[198:199], off offset:512
	s_waitcnt vmcnt(6)
	v_pk_fma_f32 v[214:215], v[222:223], v[196:197], v[214:215]
	v_pk_fma_f32 v[212:213], v[220:221], v[194:195], v[212:213]
	v_pk_fma_f32 v[218:219], v[226:227], v[196:197], v[218:219]
	v_pk_fma_f32 v[216:217], v[224:225], v[194:195], v[216:217]
	global_store_dwordx4 v[174:175], v[212:215], off offset:512
	global_store_dwordx4 v[176:177], v[216:219], off offset:512
	ds_bpermute_b32 v228, v184, v130
	ds_bpermute_b32 v229, v184, v120
	ds_bpermute_b32 v230, v184, v131
	ds_bpermute_b32 v231, v184, v121
	s_waitcnt lgkmcnt(0)
;     __device__ __forceinline__ void operator()(const pg8::f32x4 (&acc)[2][2][4][2], const pg8::Unit& u, int wr, int wc, int fr, int fq) const {
;     ...
;         for (int ai = 0; ai < 2; ++ai)
; #pragma unroll
;             for (int m = 0; m < 4; ++m) {
;                 float* rowp = base + (size_t)(ai * 128 + wr * 64 + m * 16 + fr) * DM + col0;
; #pragma unroll
;                 for (int bj = 0; bj < 2; ++bj)
; #pragma unroll
;                     for (int n = 0; n < 2; ++n) {
;                         pg8::f32x4* p = (pg8::f32x4*)(rowp + bj * 128 + n * 16);
;                         pg8::f32x4 xv = *p; xv = xv + gv[bj][n] * acc[ai][bj][m][n]; *p = xv;
;                     }
;                 if (m & 1) asm volatile("" ::: "memory");
	v_bfi_b32 v220, v188, v229, v228
	v_bfi_b32 v221, v188, v231, v230
	ds_bpermute_b32 v228, v184, v132
	ds_bpermute_b32 v229, v184, v122
	ds_bpermute_b32 v230, v184, v133
	ds_bpermute_b32 v231, v184, v123
	s_waitcnt lgkmcnt(0)
	v_bfi_b32 v222, v188, v229, v228
	v_bfi_b32 v223, v188, v231, v230
	ds_bpermute_b32 v228, v185, v130
	ds_bpermute_b32 v229, v185, v120
	ds_bpermute_b32 v230, v185, v131
	ds_bpermute_b32 v231, v185, v121
	s_waitcnt lgkmcnt(0)
	v_bfi_b32 v224, v188, v229, v228
	v_bfi_b32 v225, v188, v231, v230
	ds_bpermute_b32 v228, v185, v132
	ds_bpermute_b32 v229, v185, v122
	ds_bpermute_b32 v230, v185, v133
	ds_bpermute_b32 v231, v185, v123
	s_waitcnt lgkmcnt(0)
	v_bfi_b32 v226, v188, v229, v228
	v_bfi_b32 v227, v188, v231, v230
	v_lshl_add_u64 v[178:179], v[168:169], 0, v[152:153]
	ds_bpermute_b32 v174, v184, v178
	ds_bpermute_b32 v175, v184, v179
	ds_bpermute_b32 v176, v185, v178
	ds_bpermute_b32 v177, v185, v179
	s_waitcnt lgkmcnt(0)
	v_lshl_add_u64 v[174:175], v[174:175], 0, v[186:187]
	v_lshl_add_u64 v[176:177], v[176:177], 0, v[186:187]
	global_load_dwordx4 v[130:133], v[174:175], off
	global_load_dwordx4 v[120:123], v[176:177], off
	s_waitcnt vmcnt(8)
	v_pk_fma_f32 v[144:145], v[222:223], v[192:193], v[144:145]
	v_pk_fma_f32 v[142:143], v[220:221], v[190:191], v[142:143]
	v_pk_fma_f32 v[140:141], v[226:227], v[192:193], v[140:141]
	v_pk_fma_f32 v[138:139], v[224:225], v[190:191], v[138:139]
	global_store_dwordx4 v[180:181], v[142:145], off
	global_store_dwordx4 v[198:199], v[138:141], off
	ds_bpermute_b32 v228, v184, v116
	ds_bpermute_b32 v229, v184, v112
	ds_bpermute_b32 v230, v184, v117
	ds_bpermute_b32 v231, v184, v113
	s_waitcnt lgkmcnt(0)
	v_bfi_b32 v220, v188, v229, v228
	v_bfi_b32 v221, v188, v231, v230
	ds_bpermute_b32 v228, v184, v118
	ds_bpermute_b32 v229, v184, v114
	ds_bpermute_b32 v230, v184, v119
	ds_bpermute_b32 v231, v184, v115
	s_waitcnt lgkmcnt(0)
	v_bfi_b32 v222, v188, v229, v228
	v_bfi_b32 v223, v188, v231, v230
	ds_bpermute_b32 v228, v185, v116
	ds_bpermute_b32 v229, v185, v112
	ds_bpermute_b32 v230, v185, v117
	ds_bpermute_b32 v231, v185, v113
	s_waitcnt lgkmcnt(0)
	v_bfi_b32 v224, v188, v229, v228
	v_bfi_b32 v225, v188, v231, v230
	ds_bpermute_b32 v228, v185, v118
	ds_bpermute_b32 v229, v185, v114
	ds_bpermute_b32 v230, v185, v119
	ds_bpermute_b32 v231, v185, v115
	s_waitcnt lgkmcnt(0)
	v_bfi_b32 v226, v188, v229, v228
	v_bfi_b32 v227, v188, v231, v230
	global_load_dwordx4 v[116:119], v[174:175], off offset:512
	global_load_dwordx4 v[112:115], v[176:177], off offset:512
	s_waitcnt vmcnt(8)
	v_pk_fma_f32 v[136:137], v[222:223], v[196:197], v[136:137]
	v_pk_fma_f32 v[134:135], v[220:221], v[194:195], v[134:135]
	v_pk_fma_f32 v[126:127], v[226:227], v[196:197], v[126:127]
	v_pk_fma_f32 v[124:125], v[224:225], v[194:195], v[124:125]
	global_store_dwordx4 v[180:181], v[134:137], off offset:512
	global_store_dwordx4 v[198:199], v[124:127], off offset:512
	ds_bpermute_b32 v228, v184, v96
	ds_bpermute_b32 v229, v184, v92
	ds_bpermute_b32 v230, v184, v97
	ds_bpermute_b32 v231, v184, v93
	s_waitcnt lgkmcnt(0)
	v_bfi_b32 v220, v188, v229, v228
	v_bfi_b32 v221, v188, v231, v230
	ds_bpermute_b32 v228, v184, v98
	ds_bpermute_b32 v229, v184, v94
	ds_bpermute_b32 v230, v184, v99
	ds_bpermute_b32 v231, v184, v95
	s_waitcnt lgkmcnt(0)
	v_bfi_b32 v222, v188, v229, v228
	v_bfi_b32 v223, v188, v231, v230
	ds_bpermute_b32 v228, v185, v96
	ds_bpermute_b32 v229, v185, v92
	ds_bpermute_b32 v230, v185, v97
	ds_bpermute_b32 v231, v185, v93
	s_waitcnt lgkmcnt(0)
	v_bfi_b32 v224, v188, v229, v228
	v_bfi_b32 v225, v188, v231, v230
	ds_bpermute_b32 v228, v185, v98
	ds_bpermute_b32 v229, v185, v94
	ds_bpermute_b32 v230, v185, v99
	ds_bpermute_b32 v231, v185, v95
	s_waitcnt lgkmcnt(0)
	v_bfi_b32 v226, v188, v229, v228
	v_bfi_b32 v227, v188, v231, v230
	v_lshl_add_u64 v[178:179], v[168:169], 0, v[154:155]
	ds_bpermute_b32 v180, v184, v178
	ds_bpermute_b32 v181, v184, v179
	ds_bpermute_b32 v198, v185, v178
	ds_bpermute_b32 v199, v185, v179
	s_waitcnt lgkmcnt(0)
	v_lshl_add_u64 v[180:181], v[180:181], 0, v[186:187]
	v_lshl_add_u64 v[198:199], v[198:199], 0, v[186:187]
	global_load_dwordx4 v[96:99], v[180:181], off
	global_load_dwordx4 v[92:95], v[198:199], off
	s_waitcnt vmcnt(8)
	v_pk_fma_f32 v[132:133], v[222:223], v[192:193], v[132:133]
	v_pk_fma_f32 v[130:131], v[220:221], v[190:191], v[130:131]
	v_pk_fma_f32 v[122:123], v[226:227], v[192:193], v[122:123]
	v_pk_fma_f32 v[120:121], v[224:225], v[190:191], v[120:121]
	global_store_dwordx4 v[174:175], v[130:133], off
	global_store_dwordx4 v[176:177], v[120:123], off
	ds_bpermute_b32 v228, v184, v84
	ds_bpermute_b32 v229, v184, v76
	ds_bpermute_b32 v230, v184, v85
	ds_bpermute_b32 v231, v184, v77
	s_waitcnt lgkmcnt(0)
	v_bfi_b32 v220, v188, v229, v228
	v_bfi_b32 v221, v188, v231, v230
	ds_bpermute_b32 v228, v184, v86
	ds_bpermute_b32 v229, v184, v78
	ds_bpermute_b32 v230, v184, v87
	ds_bpermute_b32 v231, v184, v79
	s_waitcnt lgkmcnt(0)
	v_bfi_b32 v222, v188, v229, v228
	v_bfi_b32 v223, v188, v231, v230
	ds_bpermute_b32 v228, v185, v84
	ds_bpermute_b32 v229, v185, v76
	ds_bpermute_b32 v230, v185, v85
	ds_bpermute_b32 v231, v185, v77
	s_waitcnt lgkmcnt(0)
	v_bfi_b32 v224, v188, v229, v228
	v_bfi_b32 v225, v188, v231, v230
	ds_bpermute_b32 v228, v185, v86
	ds_bpermute_b32 v229, v185, v78
	ds_bpermute_b32 v230, v185, v87
	ds_bpermute_b32 v231, v185, v79
	s_waitcnt lgkmcnt(0)
	v_bfi_b32 v226, v188, v229, v228
	v_bfi_b32 v227, v188, v231, v230
	global_load_dwordx4 v[84:87], v[180:181], off offset:512
	global_load_dwordx4 v[76:79], v[198:199], off offset:512
	s_waitcnt vmcnt(8)
;     __device__ __forceinline__ void operator()(const pg8::f32x4 (&acc)[2][2][4][2], const pg8::Unit& u, int wr, int wc, int fr, int fq) const {
;     ...
;         for (int ai = 0; ai < 2; ++ai)
; #pragma unroll
;             for (int m = 0; m < 4; ++m) {
;                 float* rowp = base + (size_t)(ai * 128 + wr * 64 + m * 16 + fr) * DM + col0;
; #pragma unroll
;                 for (int bj = 0; bj < 2; ++bj)
; #pragma unroll
;                     for (int n = 0; n < 2; ++n) {
;                         pg8::f32x4* p = (pg8::f32x4*)(rowp + bj * 128 + n * 16);
;                         pg8::f32x4 xv = *p; xv = xv + gv[bj][n] * acc[ai][bj][m][n]; *p = xv;
;                     }
	v_pk_fma_f32 v[118:119], v[222:223], v[196:197], v[118:119]
	v_pk_fma_f32 v[116:117], v[220:221], v[194:195], v[116:117]
	v_pk_fma_f32 v[114:115], v[226:227], v[196:197], v[114:115]
	v_pk_fma_f32 v[112:113], v[224:225], v[194:195], v[112:113]
	global_store_dwordx4 v[174:175], v[116:119], off offset:512
	global_store_dwordx4 v[176:177], v[112:115], off offset:512
	ds_bpermute_b32 v228, v184, v80
	ds_bpermute_b32 v229, v184, v72
	ds_bpermute_b32 v230, v184, v81
	ds_bpermute_b32 v231, v184, v73
	s_waitcnt lgkmcnt(0)
	v_bfi_b32 v220, v188, v229, v228
	v_bfi_b32 v221, v188, v231, v230
	ds_bpermute_b32 v228, v184, v82
	ds_bpermute_b32 v229, v184, v74
	ds_bpermute_b32 v230, v184, v83
	ds_bpermute_b32 v231, v184, v75
	s_waitcnt lgkmcnt(0)
	v_bfi_b32 v222, v188, v229, v228
	v_bfi_b32 v223, v188, v231, v230
	ds_bpermute_b32 v228, v185, v80
	ds_bpermute_b32 v229, v185, v72
	ds_bpermute_b32 v230, v185, v81
	ds_bpermute_b32 v231, v185, v73
	s_waitcnt lgkmcnt(0)
	v_bfi_b32 v224, v188, v229, v228
	v_bfi_b32 v225, v188, v231, v230
	ds_bpermute_b32 v228, v185, v82
	ds_bpermute_b32 v229, v185, v74
	ds_bpermute_b32 v230, v185, v83
	ds_bpermute_b32 v231, v185, v75
	s_waitcnt lgkmcnt(0)
	v_bfi_b32 v226, v188, v229, v228
	v_bfi_b32 v227, v188, v231, v230
	v_lshl_add_u64 v[178:179], v[168:169], 0, v[156:157]
	ds_bpermute_b32 v174, v184, v178
	ds_bpermute_b32 v175, v184, v179
	ds_bpermute_b32 v176, v185, v178
	ds_bpermute_b32 v177, v185, v179
	s_waitcnt lgkmcnt(0)
	v_lshl_add_u64 v[174:175], v[174:175], 0, v[186:187]
	v_lshl_add_u64 v[176:177], v[176:177], 0, v[186:187]
	global_load_dwordx4 v[80:83], v[174:175], off
	global_load_dwordx4 v[72:75], v[176:177], off
	s_waitcnt vmcnt(8)
	v_pk_fma_f32 v[98:99], v[222:223], v[192:193], v[98:99]
	v_pk_fma_f32 v[96:97], v[220:221], v[190:191], v[96:97]
	v_pk_fma_f32 v[94:95], v[226:227], v[192:193], v[94:95]
	v_pk_fma_f32 v[92:93], v[224:225], v[190:191], v[92:93]
	global_store_dwordx4 v[180:181], v[96:99], off
	global_store_dwordx4 v[198:199], v[92:95], off
	ds_bpermute_b32 v228, v184, v68
	ds_bpermute_b32 v229, v184, v64
	ds_bpermute_b32 v230, v184, v69
	ds_bpermute_b32 v231, v184, v65
	s_waitcnt lgkmcnt(0)
	v_bfi_b32 v220, v188, v229, v228
	v_bfi_b32 v221, v188, v231, v230
	ds_bpermute_b32 v228, v184, v70
	ds_bpermute_b32 v229, v184, v66
	ds_bpermute_b32 v230, v184, v71
	ds_bpermute_b32 v231, v184, v67
	s_waitcnt lgkmcnt(0)
	v_bfi_b32 v222, v188, v229, v228
	v_bfi_b32 v223, v188, v231, v230
	ds_bpermute_b32 v228, v185, v68
	ds_bpermute_b32 v229, v185, v64
	ds_bpermute_b32 v230, v185, v69
	ds_bpermute_b32 v231, v185, v65
	s_waitcnt lgkmcnt(0)
	v_bfi_b32 v224, v188, v229, v228
	v_bfi_b32 v225, v188, v231, v230
	ds_bpermute_b32 v228, v185, v70
	ds_bpermute_b32 v229, v185, v66
	ds_bpermute_b32 v230, v185, v71
	ds_bpermute_b32 v231, v185, v67
	s_waitcnt lgkmcnt(0)
	v_bfi_b32 v226, v188, v229, v228
	v_bfi_b32 v227, v188, v231, v230
	global_load_dwordx4 v[68:71], v[174:175], off offset:512
	global_load_dwordx4 v[64:67], v[176:177], off offset:512
	s_waitcnt vmcnt(8)
	v_pk_fma_f32 v[86:87], v[222:223], v[196:197], v[86:87]
	v_pk_fma_f32 v[84:85], v[220:221], v[194:195], v[84:85]
	v_pk_fma_f32 v[78:79], v[226:227], v[196:197], v[78:79]
	v_pk_fma_f32 v[76:77], v[224:225], v[194:195], v[76:77]
	global_store_dwordx4 v[180:181], v[84:87], off offset:512
	global_store_dwordx4 v[198:199], v[76:79], off offset:512
	ds_bpermute_b32 v228, v184, v60
	ds_bpermute_b32 v229, v184, v56
	ds_bpermute_b32 v230, v184, v61
	ds_bpermute_b32 v231, v184, v57
	s_waitcnt lgkmcnt(0)
	v_bfi_b32 v220, v188, v229, v228
	v_bfi_b32 v221, v188, v231, v230
	ds_bpermute_b32 v228, v184, v62
	ds_bpermute_b32 v229, v184, v58
	ds_bpermute_b32 v230, v184, v63
	ds_bpermute_b32 v231, v184, v59
	s_waitcnt lgkmcnt(0)
	v_bfi_b32 v222, v188, v229, v228
	v_bfi_b32 v223, v188, v231, v230
	ds_bpermute_b32 v228, v185, v60
	ds_bpermute_b32 v229, v185, v56
	ds_bpermute_b32 v230, v185, v61
	ds_bpermute_b32 v231, v185, v57
	s_waitcnt lgkmcnt(0)
	v_bfi_b32 v224, v188, v229, v228
	v_bfi_b32 v225, v188, v231, v230
	ds_bpermute_b32 v228, v185, v62
	ds_bpermute_b32 v229, v185, v58
	ds_bpermute_b32 v230, v185, v63
	ds_bpermute_b32 v231, v185, v59
	s_waitcnt lgkmcnt(0)
	v_bfi_b32 v226, v188, v229, v228
	v_bfi_b32 v227, v188, v231, v230
	v_lshl_add_u64 v[178:179], v[168:169], 0, v[158:159]
	ds_bpermute_b32 v180, v184, v178
	ds_bpermute_b32 v181, v184, v179
	ds_bpermute_b32 v198, v185, v178
	ds_bpermute_b32 v199, v185, v179
	s_waitcnt lgkmcnt(0)
	v_lshl_add_u64 v[180:181], v[180:181], 0, v[186:187]
	v_lshl_add_u64 v[198:199], v[198:199], 0, v[186:187]
	global_load_dwordx4 v[60:63], v[180:181], off
	global_load_dwordx4 v[56:59], v[198:199], off
	s_waitcnt vmcnt(8)
	v_pk_fma_f32 v[82:83], v[222:223], v[192:193], v[82:83]
	v_pk_fma_f32 v[80:81], v[220:221], v[190:191], v[80:81]
	v_pk_fma_f32 v[74:75], v[226:227], v[192:193], v[74:75]
	v_pk_fma_f32 v[72:73], v[224:225], v[190:191], v[72:73]
	global_store_dwordx4 v[174:175], v[80:83], off
	global_store_dwordx4 v[176:177], v[72:75], off
	ds_bpermute_b32 v228, v184, v52
	ds_bpermute_b32 v229, v184, v44
	ds_bpermute_b32 v230, v184, v53
	ds_bpermute_b32 v231, v184, v45
	s_waitcnt lgkmcnt(0)
	v_bfi_b32 v220, v188, v229, v228
	v_bfi_b32 v221, v188, v231, v230
	ds_bpermute_b32 v228, v184, v54
	ds_bpermute_b32 v229, v184, v46
	ds_bpermute_b32 v230, v184, v55
	ds_bpermute_b32 v231, v184, v47
	s_waitcnt lgkmcnt(0)
	v_bfi_b32 v222, v188, v229, v228
	v_bfi_b32 v223, v188, v231, v230
	ds_bpermute_b32 v228, v185, v52
	ds_bpermute_b32 v229, v185, v44
	ds_bpermute_b32 v230, v185, v53
	ds_bpermute_b32 v231, v185, v45
	s_waitcnt lgkmcnt(0)
;     __device__ __forceinline__ void operator()(const pg8::f32x4 (&acc)[2][2][4][2], const pg8::Unit& u, int wr, int wc, int fr, int fq) const {
;     ...
;         for (int ai = 0; ai < 2; ++ai)
; #pragma unroll
;             for (int m = 0; m < 4; ++m) {
;                 float* rowp = base + (size_t)(ai * 128 + wr * 64 + m * 16 + fr) * DM + col0;
; #pragma unroll
;                 for (int bj = 0; bj < 2; ++bj)
; #pragma unroll
;                     for (int n = 0; n < 2; ++n) {
;                         pg8::f32x4* p = (pg8::f32x4*)(rowp + bj * 128 + n * 16);
;                         pg8::f32x4 xv = *p; xv = xv + gv[bj][n] * acc[ai][bj][m][n]; *p = xv;
;                     }
	v_bfi_b32 v224, v188, v229, v228
	v_bfi_b32 v225, v188, v231, v230
	ds_bpermute_b32 v228, v185, v54
	ds_bpermute_b32 v229, v185, v46
	ds_bpermute_b32 v230, v185, v55
	ds_bpermute_b32 v231, v185, v47
	s_waitcnt lgkmcnt(0)
	v_bfi_b32 v226, v188, v229, v228
	v_bfi_b32 v227, v188, v231, v230
	global_load_dwordx4 v[52:55], v[180:181], off offset:512
	global_load_dwordx4 v[44:47], v[198:199], off offset:512
	s_waitcnt vmcnt(8)
	v_pk_fma_f32 v[70:71], v[222:223], v[196:197], v[70:71]
	v_pk_fma_f32 v[68:69], v[220:221], v[194:195], v[68:69]
	v_pk_fma_f32 v[66:67], v[226:227], v[196:197], v[66:67]
	v_pk_fma_f32 v[64:65], v[224:225], v[194:195], v[64:65]
	global_store_dwordx4 v[174:175], v[68:71], off offset:512
	global_store_dwordx4 v[176:177], v[64:67], off offset:512
	ds_bpermute_b32 v228, v184, v48
	ds_bpermute_b32 v229, v184, v40
	ds_bpermute_b32 v230, v184, v49
	ds_bpermute_b32 v231, v184, v41
	s_waitcnt lgkmcnt(0)
	v_bfi_b32 v220, v188, v229, v228
	v_bfi_b32 v221, v188, v231, v230
	ds_bpermute_b32 v228, v184, v50
	ds_bpermute_b32 v229, v184, v42
	ds_bpermute_b32 v230, v184, v51
	ds_bpermute_b32 v231, v184, v43
	s_waitcnt lgkmcnt(0)
	v_bfi_b32 v222, v188, v229, v228
	v_bfi_b32 v223, v188, v231, v230
	ds_bpermute_b32 v228, v185, v48
	ds_bpermute_b32 v229, v185, v40
	ds_bpermute_b32 v230, v185, v49
	ds_bpermute_b32 v231, v185, v41
	s_waitcnt lgkmcnt(0)
	v_bfi_b32 v224, v188, v229, v228
	v_bfi_b32 v225, v188, v231, v230
	ds_bpermute_b32 v228, v185, v50
	ds_bpermute_b32 v229, v185, v42
	ds_bpermute_b32 v230, v185, v51
	ds_bpermute_b32 v231, v185, v43
	s_waitcnt lgkmcnt(0)
	v_bfi_b32 v226, v188, v229, v228
	v_bfi_b32 v227, v188, v231, v230
	v_lshl_add_u64 v[178:179], v[168:169], 0, v[160:161]
	ds_bpermute_b32 v174, v184, v178
	ds_bpermute_b32 v175, v184, v179
	ds_bpermute_b32 v176, v185, v178
	ds_bpermute_b32 v177, v185, v179
	s_waitcnt lgkmcnt(0)
	v_lshl_add_u64 v[174:175], v[174:175], 0, v[186:187]
	v_lshl_add_u64 v[176:177], v[176:177], 0, v[186:187]
	global_load_dwordx4 v[48:51], v[174:175], off
	global_load_dwordx4 v[40:43], v[176:177], off
	s_waitcnt vmcnt(8)
	v_pk_fma_f32 v[62:63], v[222:223], v[192:193], v[62:63]
	v_pk_fma_f32 v[60:61], v[220:221], v[190:191], v[60:61]
	v_pk_fma_f32 v[58:59], v[226:227], v[192:193], v[58:59]
	v_pk_fma_f32 v[56:57], v[224:225], v[190:191], v[56:57]
	global_store_dwordx4 v[180:181], v[60:63], off
	global_store_dwordx4 v[198:199], v[56:59], off
	ds_bpermute_b32 v228, v184, v36
	ds_bpermute_b32 v229, v184, v32
	ds_bpermute_b32 v230, v184, v37
	ds_bpermute_b32 v231, v184, v33
	s_waitcnt lgkmcnt(0)
	v_bfi_b32 v220, v188, v229, v228
	v_bfi_b32 v221, v188, v231, v230
	ds_bpermute_b32 v228, v184, v38
	ds_bpermute_b32 v229, v184, v34
	ds_bpermute_b32 v230, v184, v39
	ds_bpermute_b32 v231, v184, v35
	s_waitcnt lgkmcnt(0)
	v_bfi_b32 v222, v188, v229, v228
	v_bfi_b32 v223, v188, v231, v230
	ds_bpermute_b32 v228, v185, v36
	ds_bpermute_b32 v229, v185, v32
	ds_bpermute_b32 v230, v185, v37
	ds_bpermute_b32 v231, v185, v33
	s_waitcnt lgkmcnt(0)
	v_bfi_b32 v224, v188, v229, v228
	v_bfi_b32 v225, v188, v231, v230
	ds_bpermute_b32 v228, v185, v38
	ds_bpermute_b32 v229, v185, v34
	ds_bpermute_b32 v230, v185, v39
	ds_bpermute_b32 v231, v185, v35
	s_waitcnt lgkmcnt(0)
	v_bfi_b32 v226, v188, v229, v228
	v_bfi_b32 v227, v188, v231, v230
	global_load_dwordx4 v[36:39], v[174:175], off offset:512
	global_load_dwordx4 v[32:35], v[176:177], off offset:512
	s_waitcnt vmcnt(8)
	v_pk_fma_f32 v[54:55], v[222:223], v[196:197], v[54:55]
	v_pk_fma_f32 v[52:53], v[220:221], v[194:195], v[52:53]
	v_pk_fma_f32 v[46:47], v[226:227], v[196:197], v[46:47]
	v_pk_fma_f32 v[44:45], v[224:225], v[194:195], v[44:45]
	global_store_dwordx4 v[180:181], v[52:55], off offset:512
	global_store_dwordx4 v[198:199], v[44:47], off offset:512
	ds_bpermute_b32 v228, v184, v28
	ds_bpermute_b32 v229, v184, v24
	ds_bpermute_b32 v230, v184, v29
	ds_bpermute_b32 v231, v184, v25
	s_waitcnt lgkmcnt(0)
	v_bfi_b32 v220, v188, v229, v228
	v_bfi_b32 v221, v188, v231, v230
	ds_bpermute_b32 v228, v184, v30
	ds_bpermute_b32 v229, v184, v26
	ds_bpermute_b32 v230, v184, v31
	ds_bpermute_b32 v231, v184, v27
	s_waitcnt lgkmcnt(0)
	v_bfi_b32 v222, v188, v229, v228
	v_bfi_b32 v223, v188, v231, v230
	ds_bpermute_b32 v228, v185, v28
	ds_bpermute_b32 v229, v185, v24
	ds_bpermute_b32 v230, v185, v29
	ds_bpermute_b32 v231, v185, v25
	s_waitcnt lgkmcnt(0)
	v_bfi_b32 v224, v188, v229, v228
	v_bfi_b32 v225, v188, v231, v230
	ds_bpermute_b32 v228, v185, v30
	ds_bpermute_b32 v229, v185, v26
	ds_bpermute_b32 v230, v185, v31
	ds_bpermute_b32 v231, v185, v27
	s_waitcnt lgkmcnt(0)
; #define PG8_BAR __builtin_amdgcn_s_barrier()
; template <class Epi, class Sched, bool ALIGN_EPI = false, bool SP2 = false>
; __device__ __forceinline__ void gemm_phase(PG8_LAS unsigned char* lds, const Gemm g, const Sched& S, const Epi& E) {
;     ...
;         if (!has_next) break;
; #pragma unroll
;         for (int a = 0; a < 2; ++a)
; #pragma unroll
;             for (int b = 0; b < 2; ++b)
; #pragma unroll
;                 for (int m = 0; m < 4; ++m)
; #pragma unroll
;                     for (int n = 0; n < 2; ++n) acc[a][b][m][n] = (f32x4){0.f, 0.f, 0.f, 0.f};
;         cur = nxt; cA = nA; cB = nB; ++ui;
;         if constexpr (ALIGN_EPI) { if (wr == 1) PG8_BAR; }
;     __device__ __forceinline__ void operator()(const pg8::f32x4 (&acc)[2][2][4][2], const pg8::Unit& u, int wr, int wc, int fr, int fq) const {
;     ...
;         for (int ai = 0; ai < 2; ++ai)
; #pragma unroll
;             for (int m = 0; m < 4; ++m) {
;                 float* rowp = base + (size_t)(ai * 128 + wr * 64 + m * 16 + fr) * DM + col0;
; #pragma unroll
;                 for (int bj = 0; bj < 2; ++bj)
; #pragma unroll
;                     for (int n = 0; n < 2; ++n) {
;                         pg8::f32x4* p = (pg8::f32x4*)(rowp + bj * 128 + n * 16);
;                         pg8::f32x4 xv = *p; xv = xv + gv[bj][n] * acc[ai][bj][m][n]; *p = xv;
;                     }
;                 if (m & 1) asm volatile("" ::: "memory");
	v_bfi_b32 v226, v188, v229, v228
	v_bfi_b32 v227, v188, v231, v230
	v_lshl_add_u64 v[178:179], v[168:169], 0, v[162:163]
	ds_bpermute_b32 v180, v184, v178
	ds_bpermute_b32 v181, v184, v179
	ds_bpermute_b32 v198, v185, v178
	ds_bpermute_b32 v199, v185, v179
	s_waitcnt lgkmcnt(0)
	v_lshl_add_u64 v[180:181], v[180:181], 0, v[186:187]
	v_lshl_add_u64 v[198:199], v[198:199], 0, v[186:187]
	global_load_dwordx4 v[28:31], v[180:181], off
	global_load_dwordx4 v[24:27], v[198:199], off
	s_waitcnt vmcnt(8)
	v_pk_fma_f32 v[50:51], v[222:223], v[192:193], v[50:51]
	v_pk_fma_f32 v[48:49], v[220:221], v[190:191], v[48:49]
	v_pk_fma_f32 v[42:43], v[226:227], v[192:193], v[42:43]
	v_pk_fma_f32 v[40:41], v[224:225], v[190:191], v[40:41]
	global_store_dwordx4 v[174:175], v[48:51], off
	global_store_dwordx4 v[176:177], v[40:43], off
	ds_bpermute_b32 v228, v184, v20
	ds_bpermute_b32 v229, v184, v12
	ds_bpermute_b32 v230, v184, v21
	ds_bpermute_b32 v231, v184, v13
	s_waitcnt lgkmcnt(0)
	v_bfi_b32 v220, v188, v229, v228
	v_bfi_b32 v221, v188, v231, v230
	ds_bpermute_b32 v228, v184, v22
	ds_bpermute_b32 v229, v184, v14
	ds_bpermute_b32 v230, v184, v23
	ds_bpermute_b32 v231, v184, v15
	s_waitcnt lgkmcnt(0)
	v_bfi_b32 v222, v188, v229, v228
	v_bfi_b32 v223, v188, v231, v230
	ds_bpermute_b32 v228, v185, v20
	ds_bpermute_b32 v229, v185, v12
	ds_bpermute_b32 v230, v185, v21
	ds_bpermute_b32 v231, v185, v13
	s_waitcnt lgkmcnt(0)
	v_bfi_b32 v224, v188, v229, v228
	v_bfi_b32 v225, v188, v231, v230
	ds_bpermute_b32 v228, v185, v22
	ds_bpermute_b32 v229, v185, v14
	ds_bpermute_b32 v230, v185, v23
	ds_bpermute_b32 v231, v185, v15
	s_waitcnt lgkmcnt(0)
	v_bfi_b32 v226, v188, v229, v228
	v_bfi_b32 v227, v188, v231, v230
	global_load_dwordx4 v[20:23], v[180:181], off offset:512
	global_load_dwordx4 v[12:15], v[198:199], off offset:512
	s_waitcnt vmcnt(8)
	v_pk_fma_f32 v[38:39], v[222:223], v[196:197], v[38:39]
	v_pk_fma_f32 v[36:37], v[220:221], v[194:195], v[36:37]
	v_pk_fma_f32 v[34:35], v[226:227], v[196:197], v[34:35]
	v_pk_fma_f32 v[32:33], v[224:225], v[194:195], v[32:33]
	global_store_dwordx4 v[174:175], v[36:39], off offset:512
	global_store_dwordx4 v[176:177], v[32:35], off offset:512
	ds_bpermute_b32 v228, v184, v16
	ds_bpermute_b32 v229, v184, v8
	ds_bpermute_b32 v230, v184, v17
	ds_bpermute_b32 v231, v184, v9
	s_waitcnt lgkmcnt(0)
	v_bfi_b32 v220, v188, v229, v228
	v_bfi_b32 v221, v188, v231, v230
	ds_bpermute_b32 v228, v184, v18
	ds_bpermute_b32 v229, v184, v10
	ds_bpermute_b32 v230, v184, v19
	ds_bpermute_b32 v231, v184, v11
	s_waitcnt lgkmcnt(0)
	v_bfi_b32 v222, v188, v229, v228
	v_bfi_b32 v223, v188, v231, v230
	ds_bpermute_b32 v228, v185, v16
	ds_bpermute_b32 v229, v185, v8
	ds_bpermute_b32 v230, v185, v17
	ds_bpermute_b32 v231, v185, v9
	s_waitcnt lgkmcnt(0)
	v_bfi_b32 v224, v188, v229, v228
	v_bfi_b32 v225, v188, v231, v230
	ds_bpermute_b32 v228, v185, v18
	ds_bpermute_b32 v229, v185, v10
	ds_bpermute_b32 v230, v185, v19
	ds_bpermute_b32 v231, v185, v11
	s_waitcnt lgkmcnt(0)
	v_bfi_b32 v226, v188, v229, v228
	v_bfi_b32 v227, v188, v231, v230
	s_waitcnt vmcnt(6)
	v_pk_fma_f32 v[30:31], v[222:223], v[192:193], v[30:31]
	v_pk_fma_f32 v[28:29], v[220:221], v[190:191], v[28:29]
	v_pk_fma_f32 v[26:27], v[226:227], v[192:193], v[26:27]
	v_pk_fma_f32 v[24:25], v[224:225], v[190:191], v[24:25]
	global_store_dwordx4 v[180:181], v[28:31], off
	global_store_dwordx4 v[198:199], v[24:27], off
	ds_bpermute_b32 v228, v184, v4
	ds_bpermute_b32 v229, v184, v0
	ds_bpermute_b32 v230, v184, v5
	ds_bpermute_b32 v231, v184, v1
	s_waitcnt lgkmcnt(0)
	v_bfi_b32 v220, v188, v229, v228
	v_bfi_b32 v221, v188, v231, v230
	ds_bpermute_b32 v228, v184, v6
	ds_bpermute_b32 v229, v184, v2
	ds_bpermute_b32 v230, v184, v7
	ds_bpermute_b32 v231, v184, v3
	s_waitcnt lgkmcnt(0)
	v_bfi_b32 v222, v188, v229, v228
	v_bfi_b32 v223, v188, v231, v230
	ds_bpermute_b32 v228, v185, v4
	ds_bpermute_b32 v229, v185, v0
	ds_bpermute_b32 v230, v185, v5
	ds_bpermute_b32 v231, v185, v1
	s_waitcnt lgkmcnt(0)
	v_bfi_b32 v224, v188, v229, v228
	v_bfi_b32 v225, v188, v231, v230
	ds_bpermute_b32 v228, v185, v6
	ds_bpermute_b32 v229, v185, v2
	ds_bpermute_b32 v230, v185, v7
	ds_bpermute_b32 v231, v185, v3
	s_waitcnt lgkmcnt(0)
	v_bfi_b32 v226, v188, v229, v228
	v_bfi_b32 v227, v188, v231, v230
	s_waitcnt vmcnt(4)
	v_pk_fma_f32 v[22:23], v[222:223], v[196:197], v[22:23]
	v_pk_fma_f32 v[20:21], v[220:221], v[194:195], v[20:21]
	v_pk_fma_f32 v[14:15], v[226:227], v[196:197], v[14:15]
	v_pk_fma_f32 v[12:13], v[224:225], v[194:195], v[12:13]
	global_store_dwordx4 v[180:181], v[20:23], off offset:512
	global_store_dwordx4 v[198:199], v[12:15], off offset:512
	s_cbranch_vccnz .LBB0_844
	s_andn2_b64 vcc, exec, s[10:11]
	s_cbranch_vccnz .LBB0_843
	s_barrier
	s_branch .LBB0_843

;     __device__ __forceinline__ void operator()(const pg8::f32x4 (&acc)[2][2][4][2], const pg8::Unit& u, int wr, int wc, int fr, int fq) const {
;         const int b = u.pm / 9, j = u.pm - b * 9;
;         float* base = (j == 0) ? xc + (size_t)b * CTX * DM : out + ((size_t)b * SEQ + (size_t)(j - 1) * 256) * DM;
;         const float* g = gate + (size_t)((j == 0) ? 16 : b) * MODW;
;         const int col0 = u.pn * 256 + wc * 32 + 4 * fq;
;         pg8::f32x4 gv[2][2];
; #pragma unroll
;         for (int bj = 0; bj < 2; ++bj)
; #pragma unroll
;             for (int n = 0; n < 2; ++n) gv[bj][n] = *(const pg8::f32x4*)(g + col0 + bj * 128 + n * 16);
; #pragma unroll
;         for (int ai = 0; ai < 2; ++ai)
; #pragma unroll
;             for (int m = 0; m < 4; ++m) {
;                 float* rowp = base + (size_t)(ai * 128 + wr * 64 + m * 16 + fr) * DM + col0;
; #pragma unroll
;                 for (int bj = 0; bj < 2; ++bj)
; #pragma unroll
;                     for (int n = 0; n < 2; ++n) {
;                         pg8::f32x4* p = (pg8::f32x4*)(rowp + bj * 128 + n * 16);
;                         pg8::f32x4 xv = *p; xv = xv + gv[bj][n] * acc[ai][bj][m][n]; *p = xv;
;                     }
.LBB0_880:
	s_lshl_b64 s[12:13], s[56:57], 2
	v_lshl_or_b32 v88, s62, 8, v171
	s_add_u32 s12, s41, s12
	v_ashrrev_i32_e32 v89, 31, v88
	s_addc_u32 s13, s0, s13
	v_lshlrev_b64 v[168:169], 2, v[88:89]
	v_lshl_add_u64 v[88:89], s[12:13], 0, v[168:169]
	v_lshl_add_u64 v[168:169], s[52:53], 0, v[168:169]
	v_lshl_add_u64 v[178:179], v[168:169], 0, v[148:149]
	global_load_dwordx4 v[108:111], v[88:89], off
	global_load_dwordx4 v[104:107], v[88:89], off offset:64
	global_load_dwordx4 v[100:103], v[88:89], off offset:512
	s_nop 0
	global_load_dwordx4 v[88:91], v[88:89], off offset:576
	s_mov_b64 s[52:53], -1
	s_andn2_b64 vcc, exec, s[42:43]
	s_waitcnt vmcnt(0)
	v_and_b32_e32 v228, 63, v200
	v_lshrrev_b32_e32 v229, 3, v228
	v_and_b32_e32 v184, 3, v228
	v_lshl_or_b32 v184, v184, 4, v229
	v_lshlrev_b32_e32 v184, 2, v184
	v_add_u32_e32 v185, 32, v184
	v_bfe_u32 v229, v228, 2, 1
	v_lshlrev_b32_e32 v186, 6, v229
	v_mov_b32_e32 v187, 0
	v_sub_u32_e32 v188, 0, v229
	ds_bpermute_b32 v228, v184, v108
	ds_bpermute_b32 v229, v184, v104
	s_waitcnt lgkmcnt(0)
	v_bfi_b32 v190, v188, v229, v228
	ds_bpermute_b32 v228, v184, v109
	ds_bpermute_b32 v229, v184, v105
	s_waitcnt lgkmcnt(0)
	v_bfi_b32 v191, v188, v229, v228
	ds_bpermute_b32 v228, v184, v110
	ds_bpermute_b32 v229, v184, v106
	s_waitcnt lgkmcnt(0)
	v_bfi_b32 v192, v188, v229, v228
	ds_bpermute_b32 v228, v184, v111
	ds_bpermute_b32 v229, v184, v107
	s_waitcnt lgkmcnt(0)
	v_bfi_b32 v193, v188, v229, v228
	ds_bpermute_b32 v228, v184, v100
	ds_bpermute_b32 v229, v184, v88
	s_waitcnt lgkmcnt(0)
	v_bfi_b32 v194, v188, v229, v228
	ds_bpermute_b32 v228, v184, v101
	ds_bpermute_b32 v229, v184, v89
	s_waitcnt lgkmcnt(0)
	v_bfi_b32 v195, v188, v229, v228
	ds_bpermute_b32 v228, v184, v102
	ds_bpermute_b32 v229, v184, v90
	s_waitcnt lgkmcnt(0)
	v_bfi_b32 v196, v188, v229, v228
	ds_bpermute_b32 v228, v184, v103
	ds_bpermute_b32 v229, v184, v91
	s_waitcnt lgkmcnt(0)
	v_bfi_b32 v197, v188, v229, v228
	v_lshl_add_u64 v[178:179], v[168:169], 0, v[148:149]
	ds_bpermute_b32 v174, v184, v178
	ds_bpermute_b32 v175, v184, v179
	ds_bpermute_b32 v176, v185, v178
	ds_bpermute_b32 v177, v185, v179
	s_waitcnt lgkmcnt(0)
	v_lshl_add_u64 v[174:175], v[174:175], 0, v[186:187]
	v_lshl_add_u64 v[176:177], v[176:177], 0, v[186:187]
	global_load_dwordx4 v[204:207], v[174:175], off
	global_load_dwordx4 v[208:211], v[176:177], off
	global_load_dwordx4 v[212:215], v[174:175], off offset:512
	global_load_dwordx4 v[216:219], v[176:177], off offset:512
	ds_bpermute_b32 v228, v184, v142
	ds_bpermute_b32 v229, v184, v138
	ds_bpermute_b32 v230, v184, v143
	ds_bpermute_b32 v231, v184, v139
	s_waitcnt lgkmcnt(0)
	v_bfi_b32 v220, v188, v229, v228
	v_bfi_b32 v221, v188, v231, v230
	ds_bpermute_b32 v228, v184, v144
	ds_bpermute_b32 v229, v184, v140
	ds_bpermute_b32 v230, v184, v145
	ds_bpermute_b32 v231, v184, v141
	s_waitcnt lgkmcnt(0)
	v_bfi_b32 v222, v188, v229, v228
	v_bfi_b32 v223, v188, v231, v230
	ds_bpermute_b32 v228, v185, v142
	ds_bpermute_b32 v229, v185, v138
	ds_bpermute_b32 v230, v185, v143
	ds_bpermute_b32 v231, v185, v139
	s_waitcnt lgkmcnt(0)
	v_bfi_b32 v224, v188, v229, v228
	v_bfi_b32 v225, v188, v231, v230
	ds_bpermute_b32 v228, v185, v144
	ds_bpermute_b32 v229, v185, v140
	ds_bpermute_b32 v230, v185, v145
	ds_bpermute_b32 v231, v185, v141
	s_waitcnt lgkmcnt(0)
	v_bfi_b32 v226, v188, v229, v228
	v_bfi_b32 v227, v188, v231, v230
	v_lshl_add_u64 v[178:179], v[168:169], 0, v[150:151]
	ds_bpermute_b32 v180, v184, v178
	ds_bpermute_b32 v181, v184, v179
	ds_bpermute_b32 v198, v185, v178
	ds_bpermute_b32 v199, v185, v179
	s_waitcnt lgkmcnt(0)
	v_lshl_add_u64 v[180:181], v[180:181], 0, v[186:187]
	v_lshl_add_u64 v[198:199], v[198:199], 0, v[186:187]
	global_load_dwordx4 v[142:145], v[180:181], off
	global_load_dwordx4 v[138:141], v[198:199], off
	s_waitcnt vmcnt(4)
	v_pk_fma_f32 v[206:207], v[222:223], v[192:193], v[206:207]
	v_pk_fma_f32 v[204:205], v[220:221], v[190:191], v[204:205]
	v_pk_fma_f32 v[210:211], v[226:227], v[192:193], v[210:211]
	v_pk_fma_f32 v[208:209], v[224:225], v[190:191], v[208:209]
	global_store_dwordx4 v[174:175], v[204:207], off
	global_store_dwordx4 v[176:177], v[208:211], off
	ds_bpermute_b32 v228, v184, v134
	ds_bpermute_b32 v229, v184, v124
	ds_bpermute_b32 v230, v184, v135
	ds_bpermute_b32 v231, v184, v125
	s_waitcnt lgkmcnt(0)
	v_bfi_b32 v220, v188, v229, v228
	v_bfi_b32 v221, v188, v231, v230
	ds_bpermute_b32 v228, v184, v136
	ds_bpermute_b32 v229, v184, v126
	ds_bpermute_b32 v230, v184, v137
	ds_bpermute_b32 v231, v184, v127
	s_waitcnt lgkmcnt(0)
	v_bfi_b32 v222, v188, v229, v228
	v_bfi_b32 v223, v188, v231, v230
	ds_bpermute_b32 v228, v185, v134
	ds_bpermute_b32 v229, v185, v124
	ds_bpermute_b32 v230, v185, v135
	ds_bpermute_b32 v231, v185, v125
	s_waitcnt lgkmcnt(0)
	v_bfi_b32 v224, v188, v229, v228
	v_bfi_b32 v225, v188, v231, v230
	ds_bpermute_b32 v228, v185, v136
	ds_bpermute_b32 v229, v185, v126
	ds_bpermute_b32 v230, v185, v137
	ds_bpermute_b32 v231, v185, v127
	s_waitcnt lgkmcnt(0)
	v_bfi_b32 v226, v188, v229, v228
	v_bfi_b32 v227, v188, v231, v230
	global_load_dwordx4 v[134:137], v[180:181], off offset:512
	global_load_dwordx4 v[124:127], v[198:199], off offset:512
	s_waitcnt vmcnt(6)
	v_pk_fma_f32 v[214:215], v[222:223], v[196:197], v[214:215]
	v_pk_fma_f32 v[212:213], v[220:221], v[194:195], v[212:213]
	v_pk_fma_f32 v[218:219], v[226:227], v[196:197], v[218:219]
	v_pk_fma_f32 v[216:217], v[224:225], v[194:195], v[216:217]
	global_store_dwordx4 v[174:175], v[212:215], off offset:512
	global_store_dwordx4 v[176:177], v[216:219], off offset:512
	ds_bpermute_b32 v228, v184, v130
	ds_bpermute_b32 v229, v184, v120
	ds_bpermute_b32 v230, v184, v131
	ds_bpermute_b32 v231, v184, v121
	s_waitcnt lgkmcnt(0)
;     __device__ __forceinline__ void operator()(const pg8::f32x4 (&acc)[2][2][4][2], const pg8::Unit& u, int wr, int wc, int fr, int fq) const {
;     ...
;         for (int ai = 0; ai < 2; ++ai)
; #pragma unroll
;             for (int m = 0; m < 4; ++m) {
;                 float* rowp = base + (size_t)(ai * 128 + wr * 64 + m * 16 + fr) * DM + col0;
; #pragma unroll
;                 for (int bj = 0; bj < 2; ++bj)
; #pragma unroll
;                     for (int n = 0; n < 2; ++n) {
;                         pg8::f32x4* p = (pg8::f32x4*)(rowp + bj * 128 + n * 16);
;                         pg8::f32x4 xv = *p; xv = xv + gv[bj][n] * acc[ai][bj][m][n]; *p = xv;
;                     }
	v_bfi_b32 v220, v188, v229, v228
	v_bfi_b32 v221, v188, v231, v230
	ds_bpermute_b32 v228, v184, v132
	ds_bpermute_b32 v229, v184, v122
	ds_bpermute_b32 v230, v184, v133
	ds_bpermute_b32 v231, v184, v123
	s_waitcnt lgkmcnt(0)
	v_bfi_b32 v222, v188, v229, v228
	v_bfi_b32 v223, v188, v231, v230
	ds_bpermute_b32 v228, v185, v130
	ds_bpermute_b32 v229, v185, v120
	ds_bpermute_b32 v230, v185, v131
	ds_bpermute_b32 v231, v185, v121
	s_waitcnt lgkmcnt(0)
	v_bfi_b32 v224, v188, v229, v228
	v_bfi_b32 v225, v188, v231, v230
	ds_bpermute_b32 v228, v185, v132
	ds_bpermute_b32 v229, v185, v122
	ds_bpermute_b32 v230, v185, v133
	ds_bpermute_b32 v231, v185, v123
	s_waitcnt lgkmcnt(0)
	v_bfi_b32 v226, v188, v229, v228
	v_bfi_b32 v227, v188, v231, v230
	v_lshl_add_u64 v[178:179], v[168:169], 0, v[152:153]
	ds_bpermute_b32 v174, v184, v178
	ds_bpermute_b32 v175, v184, v179
	ds_bpermute_b32 v176, v185, v178
	ds_bpermute_b32 v177, v185, v179
	s_waitcnt lgkmcnt(0)
	v_lshl_add_u64 v[174:175], v[174:175], 0, v[186:187]
	v_lshl_add_u64 v[176:177], v[176:177], 0, v[186:187]
	global_load_dwordx4 v[130:133], v[174:175], off
	global_load_dwordx4 v[120:123], v[176:177], off
	s_waitcnt vmcnt(8)
	v_pk_fma_f32 v[144:145], v[222:223], v[192:193], v[144:145]
	v_pk_fma_f32 v[142:143], v[220:221], v[190:191], v[142:143]
	v_pk_fma_f32 v[140:141], v[226:227], v[192:193], v[140:141]
	v_pk_fma_f32 v[138:139], v[224:225], v[190:191], v[138:139]
	global_store_dwordx4 v[180:181], v[142:145], off
	global_store_dwordx4 v[198:199], v[138:141], off
	ds_bpermute_b32 v228, v184, v116
	ds_bpermute_b32 v229, v184, v112
	ds_bpermute_b32 v230, v184, v117
	ds_bpermute_b32 v231, v184, v113
	s_waitcnt lgkmcnt(0)
	v_bfi_b32 v220, v188, v229, v228
	v_bfi_b32 v221, v188, v231, v230
	ds_bpermute_b32 v228, v184, v118
	ds_bpermute_b32 v229, v184, v114
	ds_bpermute_b32 v230, v184, v119
	ds_bpermute_b32 v231, v184, v115
	s_waitcnt lgkmcnt(0)
	v_bfi_b32 v222, v188, v229, v228
	v_bfi_b32 v223, v188, v231, v230
	ds_bpermute_b32 v228, v185, v116
	ds_bpermute_b32 v229, v185, v112
	ds_bpermute_b32 v230, v185, v117
	ds_bpermute_b32 v231, v185, v113
	s_waitcnt lgkmcnt(0)
	v_bfi_b32 v224, v188, v229, v228
	v_bfi_b32 v225, v188, v231, v230
	ds_bpermute_b32 v228, v185, v118
	ds_bpermute_b32 v229, v185, v114
	ds_bpermute_b32 v230, v185, v119
	ds_bpermute_b32 v231, v185, v115
	s_waitcnt lgkmcnt(0)
	v_bfi_b32 v226, v188, v229, v228
	v_bfi_b32 v227, v188, v231, v230
	global_load_dwordx4 v[116:119], v[174:175], off offset:512
	global_load_dwordx4 v[112:115], v[176:177], off offset:512
	s_waitcnt vmcnt(8)
	v_pk_fma_f32 v[136:137], v[222:223], v[196:197], v[136:137]
	v_pk_fma_f32 v[134:135], v[220:221], v[194:195], v[134:135]
	v_pk_fma_f32 v[126:127], v[226:227], v[196:197], v[126:127]
	v_pk_fma_f32 v[124:125], v[224:225], v[194:195], v[124:125]
	global_store_dwordx4 v[180:181], v[134:137], off offset:512
	global_store_dwordx4 v[198:199], v[124:127], off offset:512
	ds_bpermute_b32 v228, v184, v96
	ds_bpermute_b32 v229, v184, v92
	ds_bpermute_b32 v230, v184, v97
	ds_bpermute_b32 v231, v184, v93
	s_waitcnt lgkmcnt(0)
	v_bfi_b32 v220, v188, v229, v228
	v_bfi_b32 v221, v188, v231, v230
	ds_bpermute_b32 v228, v184, v98
	ds_bpermute_b32 v229, v184, v94
	ds_bpermute_b32 v230, v184, v99
	ds_bpermute_b32 v231, v184, v95
	s_waitcnt lgkmcnt(0)
	v_bfi_b32 v222, v188, v229, v228
	v_bfi_b32 v223, v188, v231, v230
	ds_bpermute_b32 v228, v185, v96
	ds_bpermute_b32 v229, v185, v92
	ds_bpermute_b32 v230, v185, v97
	ds_bpermute_b32 v231, v185, v93
	s_waitcnt lgkmcnt(0)
	v_bfi_b32 v224, v188, v229, v228
	v_bfi_b32 v225, v188, v231, v230
	ds_bpermute_b32 v228, v185, v98
	ds_bpermute_b32 v229, v185, v94
	ds_bpermute_b32 v230, v185, v99
	ds_bpermute_b32 v231, v185, v95
	s_waitcnt lgkmcnt(0)
	v_bfi_b32 v226, v188, v229, v228
	v_bfi_b32 v227, v188, v231, v230
	v_lshl_add_u64 v[178:179], v[168:169], 0, v[154:155]
	ds_bpermute_b32 v180, v184, v178
	ds_bpermute_b32 v181, v184, v179
	ds_bpermute_b32 v198, v185, v178
	ds_bpermute_b32 v199, v185, v179
	s_waitcnt lgkmcnt(0)
	v_lshl_add_u64 v[180:181], v[180:181], 0, v[186:187]
	v_lshl_add_u64 v[198:199], v[198:199], 0, v[186:187]
	global_load_dwordx4 v[96:99], v[180:181], off
	global_load_dwordx4 v[92:95], v[198:199], off
	s_waitcnt vmcnt(8)
	v_pk_fma_f32 v[132:133], v[222:223], v[192:193], v[132:133]
	v_pk_fma_f32 v[130:131], v[220:221], v[190:191], v[130:131]
	v_pk_fma_f32 v[122:123], v[226:227], v[192:193], v[122:123]
	v_pk_fma_f32 v[120:121], v[224:225], v[190:191], v[120:121]
	global_store_dwordx4 v[174:175], v[130:133], off
	global_store_dwordx4 v[176:177], v[120:123], off
	ds_bpermute_b32 v228, v184, v84
	ds_bpermute_b32 v229, v184, v76
	ds_bpermute_b32 v230, v184, v85
	ds_bpermute_b32 v231, v184, v77
	s_waitcnt lgkmcnt(0)
	v_bfi_b32 v220, v188, v229, v228
	v_bfi_b32 v221, v188, v231, v230
	ds_bpermute_b32 v228, v184, v86
	ds_bpermute_b32 v229, v184, v78
	ds_bpermute_b32 v230, v184, v87
	ds_bpermute_b32 v231, v184, v79
	s_waitcnt lgkmcnt(0)
	v_bfi_b32 v222, v188, v229, v228
	v_bfi_b32 v223, v188, v231, v230
	ds_bpermute_b32 v228, v185, v84
	ds_bpermute_b32 v229, v185, v76
	ds_bpermute_b32 v230, v185, v85
	ds_bpermute_b32 v231, v185, v77
	s_waitcnt lgkmcnt(0)
	v_bfi_b32 v224, v188, v229, v228
	v_bfi_b32 v225, v188, v231, v230
	ds_bpermute_b32 v228, v185, v86
	ds_bpermute_b32 v229, v185, v78
	ds_bpermute_b32 v230, v185, v87
	ds_bpermute_b32 v231, v185, v79
	s_waitcnt lgkmcnt(0)
	v_bfi_b32 v226, v188, v229, v228
	v_bfi_b32 v227, v188, v231, v230
	global_load_dwordx4 v[84:87], v[180:181], off offset:512
	global_load_dwordx4 v[76:79], v[198:199], off offset:512
	s_waitcnt vmcnt(8)
;     __device__ __forceinline__ void operator()(const pg8::f32x4 (&acc)[2][2][4][2], const pg8::Unit& u, int wr, int wc, int fr, int fq) const {
;     ...
;         for (int ai = 0; ai < 2; ++ai)
; #pragma unroll
;             for (int m = 0; m < 4; ++m) {
;                 float* rowp = base + (size_t)(ai * 128 + wr * 64 + m * 16 + fr) * DM + col0;
; #pragma unroll
;                 for (int bj = 0; bj < 2; ++bj)
; #pragma unroll
;                     for (int n = 0; n < 2; ++n) {
;                         pg8::f32x4* p = (pg8::f32x4*)(rowp + bj * 128 + n * 16);
;                         pg8::f32x4 xv = *p; xv = xv + gv[bj][n] * acc[ai][bj][m][n]; *p = xv;
;                     }
	v_pk_fma_f32 v[118:119], v[222:223], v[196:197], v[118:119]
	v_pk_fma_f32 v[116:117], v[220:221], v[194:195], v[116:117]
	v_pk_fma_f32 v[114:115], v[226:227], v[196:197], v[114:115]
	v_pk_fma_f32 v[112:113], v[224:225], v[194:195], v[112:113]
	global_store_dwordx4 v[174:175], v[116:119], off offset:512
	global_store_dwordx4 v[176:177], v[112:115], off offset:512
	ds_bpermute_b32 v228, v184, v80
	ds_bpermute_b32 v229, v184, v72
	ds_bpermute_b32 v230, v184, v81
	ds_bpermute_b32 v231, v184, v73
	s_waitcnt lgkmcnt(0)
	v_bfi_b32 v220, v188, v229, v228
	v_bfi_b32 v221, v188, v231, v230
	ds_bpermute_b32 v228, v184, v82
	ds_bpermute_b32 v229, v184, v74
	ds_bpermute_b32 v230, v184, v83
	ds_bpermute_b32 v231, v184, v75
	s_waitcnt lgkmcnt(0)
	v_bfi_b32 v222, v188, v229, v228
	v_bfi_b32 v223, v188, v231, v230
	ds_bpermute_b32 v228, v185, v80
	ds_bpermute_b32 v229, v185, v72
	ds_bpermute_b32 v230, v185, v81
	ds_bpermute_b32 v231, v185, v73
	s_waitcnt lgkmcnt(0)
	v_bfi_b32 v224, v188, v229, v228
	v_bfi_b32 v225, v188, v231, v230
	ds_bpermute_b32 v228, v185, v82
	ds_bpermute_b32 v229, v185, v74
	ds_bpermute_b32 v230, v185, v83
	ds_bpermute_b32 v231, v185, v75
	s_waitcnt lgkmcnt(0)
	v_bfi_b32 v226, v188, v229, v228
	v_bfi_b32 v227, v188, v231, v230
	v_lshl_add_u64 v[178:179], v[168:169], 0, v[156:157]
	ds_bpermute_b32 v174, v184, v178
	ds_bpermute_b32 v175, v184, v179
	ds_bpermute_b32 v176, v185, v178
	ds_bpermute_b32 v177, v185, v179
	s_waitcnt lgkmcnt(0)
	v_lshl_add_u64 v[174:175], v[174:175], 0, v[186:187]
	v_lshl_add_u64 v[176:177], v[176:177], 0, v[186:187]
	global_load_dwordx4 v[80:83], v[174:175], off
	global_load_dwordx4 v[72:75], v[176:177], off
	s_waitcnt vmcnt(8)
	v_pk_fma_f32 v[98:99], v[222:223], v[192:193], v[98:99]
	v_pk_fma_f32 v[96:97], v[220:221], v[190:191], v[96:97]
	v_pk_fma_f32 v[94:95], v[226:227], v[192:193], v[94:95]
	v_pk_fma_f32 v[92:93], v[224:225], v[190:191], v[92:93]
	global_store_dwordx4 v[180:181], v[96:99], off
	global_store_dwordx4 v[198:199], v[92:95], off
	ds_bpermute_b32 v228, v184, v68
	ds_bpermute_b32 v229, v184, v64
	ds_bpermute_b32 v230, v184, v69
	ds_bpermute_b32 v231, v184, v65
	s_waitcnt lgkmcnt(0)
	v_bfi_b32 v220, v188, v229, v228
	v_bfi_b32 v221, v188, v231, v230
	ds_bpermute_b32 v228, v184, v70
	ds_bpermute_b32 v229, v184, v66
	ds_bpermute_b32 v230, v184, v71
	ds_bpermute_b32 v231, v184, v67
	s_waitcnt lgkmcnt(0)
	v_bfi_b32 v222, v188, v229, v228
	v_bfi_b32 v223, v188, v231, v230
	ds_bpermute_b32 v228, v185, v68
	ds_bpermute_b32 v229, v185, v64
	ds_bpermute_b32 v230, v185, v69
	ds_bpermute_b32 v231, v185, v65
	s_waitcnt lgkmcnt(0)
	v_bfi_b32 v224, v188, v229, v228
	v_bfi_b32 v225, v188, v231, v230
	ds_bpermute_b32 v228, v185, v70
	ds_bpermute_b32 v229, v185, v66
	ds_bpermute_b32 v230, v185, v71
	ds_bpermute_b32 v231, v185, v67
	s_waitcnt lgkmcnt(0)
	v_bfi_b32 v226, v188, v229, v228
	v_bfi_b32 v227, v188, v231, v230
	global_load_dwordx4 v[68:71], v[174:175], off offset:512
	global_load_dwordx4 v[64:67], v[176:177], off offset:512
	s_waitcnt vmcnt(8)
	v_pk_fma_f32 v[86:87], v[222:223], v[196:197], v[86:87]
	v_pk_fma_f32 v[84:85], v[220:221], v[194:195], v[84:85]
	v_pk_fma_f32 v[78:79], v[226:227], v[196:197], v[78:79]
	v_pk_fma_f32 v[76:77], v[224:225], v[194:195], v[76:77]
	global_store_dwordx4 v[180:181], v[84:87], off offset:512
	global_store_dwordx4 v[198:199], v[76:79], off offset:512
	ds_bpermute_b32 v228, v184, v60
	ds_bpermute_b32 v229, v184, v56
	ds_bpermute_b32 v230, v184, v61
	ds_bpermute_b32 v231, v184, v57
	s_waitcnt lgkmcnt(0)
	v_bfi_b32 v220, v188, v229, v228
	v_bfi_b32 v221, v188, v231, v230
	ds_bpermute_b32 v228, v184, v62
	ds_bpermute_b32 v229, v184, v58
	ds_bpermute_b32 v230, v184, v63
	ds_bpermute_b32 v231, v184, v59
	s_waitcnt lgkmcnt(0)
	v_bfi_b32 v222, v188, v229, v228
	v_bfi_b32 v223, v188, v231, v230
	ds_bpermute_b32 v228, v185, v60
	ds_bpermute_b32 v229, v185, v56
	ds_bpermute_b32 v230, v185, v61
	ds_bpermute_b32 v231, v185, v57
	s_waitcnt lgkmcnt(0)
	v_bfi_b32 v224, v188, v229, v228
	v_bfi_b32 v225, v188, v231, v230
	ds_bpermute_b32 v228, v185, v62
	ds_bpermute_b32 v229, v185, v58
	ds_bpermute_b32 v230, v185, v63
	ds_bpermute_b32 v231, v185, v59
	s_waitcnt lgkmcnt(0)
	v_bfi_b32 v226, v188, v229, v228
	v_bfi_b32 v227, v188, v231, v230
	v_lshl_add_u64 v[178:179], v[168:169], 0, v[158:159]
	ds_bpermute_b32 v180, v184, v178
	ds_bpermute_b32 v181, v184, v179
	ds_bpermute_b32 v198, v185, v178
	ds_bpermute_b32 v199, v185, v179
	s_waitcnt lgkmcnt(0)
	v_lshl_add_u64 v[180:181], v[180:181], 0, v[186:187]
	v_lshl_add_u64 v[198:199], v[198:199], 0, v[186:187]
	global_load_dwordx4 v[60:63], v[180:181], off
	global_load_dwordx4 v[56:59], v[198:199], off
	s_waitcnt vmcnt(8)
	v_pk_fma_f32 v[82:83], v[222:223], v[192:193], v[82:83]
	v_pk_fma_f32 v[80:81], v[220:221], v[190:191], v[80:81]
	v_pk_fma_f32 v[74:75], v[226:227], v[192:193], v[74:75]
	v_pk_fma_f32 v[72:73], v[224:225], v[190:191], v[72:73]
	global_store_dwordx4 v[174:175], v[80:83], off
	global_store_dwordx4 v[176:177], v[72:75], off
	ds_bpermute_b32 v228, v184, v52
	ds_bpermute_b32 v229, v184, v44
	ds_bpermute_b32 v230, v184, v53
	ds_bpermute_b32 v231, v184, v45
	s_waitcnt lgkmcnt(0)
	v_bfi_b32 v220, v188, v229, v228
	v_bfi_b32 v221, v188, v231, v230
	ds_bpermute_b32 v228, v184, v54
	ds_bpermute_b32 v229, v184, v46
	ds_bpermute_b32 v230, v184, v55
	ds_bpermute_b32 v231, v184, v47
	s_waitcnt lgkmcnt(0)
	v_bfi_b32 v222, v188, v229, v228
	v_bfi_b32 v223, v188, v231, v230
	ds_bpermute_b32 v228, v185, v52
	ds_bpermute_b32 v229, v185, v44
	ds_bpermute_b32 v230, v185, v53
	ds_bpermute_b32 v231, v185, v45
	s_waitcnt lgkmcnt(0)
;     __device__ __forceinline__ void operator()(const pg8::f32x4 (&acc)[2][2][4][2], const pg8::Unit& u, int wr, int wc, int fr, int fq) const {
;     ...
;         for (int ai = 0; ai < 2; ++ai)
; #pragma unroll
;             for (int m = 0; m < 4; ++m) {
;                 float* rowp = base + (size_t)(ai * 128 + wr * 64 + m * 16 + fr) * DM + col0;
; #pragma unroll
;                 for (int bj = 0; bj < 2; ++bj)
; #pragma unroll
;                     for (int n = 0; n < 2; ++n) {
;                         pg8::f32x4* p = (pg8::f32x4*)(rowp + bj * 128 + n * 16);
;                         pg8::f32x4 xv = *p; xv = xv + gv[bj][n] * acc[ai][bj][m][n]; *p = xv;
;                     }
	v_bfi_b32 v224, v188, v229, v228
	v_bfi_b32 v225, v188, v231, v230
	ds_bpermute_b32 v228, v185, v54
	ds_bpermute_b32 v229, v185, v46
	ds_bpermute_b32 v230, v185, v55
	ds_bpermute_b32 v231, v185, v47
	s_waitcnt lgkmcnt(0)
	v_bfi_b32 v226, v188, v229, v228
	v_bfi_b32 v227, v188, v231, v230
	global_load_dwordx4 v[52:55], v[180:181], off offset:512
	global_load_dwordx4 v[44:47], v[198:199], off offset:512
	s_waitcnt vmcnt(8)
	v_pk_fma_f32 v[70:71], v[222:223], v[196:197], v[70:71]
	v_pk_fma_f32 v[68:69], v[220:221], v[194:195], v[68:69]
	v_pk_fma_f32 v[66:67], v[226:227], v[196:197], v[66:67]
	v_pk_fma_f32 v[64:65], v[224:225], v[194:195], v[64:65]
	global_store_dwordx4 v[174:175], v[68:71], off offset:512
	global_store_dwordx4 v[176:177], v[64:67], off offset:512
	ds_bpermute_b32 v228, v184, v48
	ds_bpermute_b32 v229, v184, v40
	ds_bpermute_b32 v230, v184, v49
	ds_bpermute_b32 v231, v184, v41
	s_waitcnt lgkmcnt(0)
	v_bfi_b32 v220, v188, v229, v228
	v_bfi_b32 v221, v188, v231, v230
	ds_bpermute_b32 v228, v184, v50
	ds_bpermute_b32 v229, v184, v42
	ds_bpermute_b32 v230, v184, v51
	ds_bpermute_b32 v231, v184, v43
	s_waitcnt lgkmcnt(0)
	v_bfi_b32 v222, v188, v229, v228
	v_bfi_b32 v223, v188, v231, v230
	ds_bpermute_b32 v228, v185, v48
	ds_bpermute_b32 v229, v185, v40
	ds_bpermute_b32 v230, v185, v49
	ds_bpermute_b32 v231, v185, v41
	s_waitcnt lgkmcnt(0)
	v_bfi_b32 v224, v188, v229, v228
	v_bfi_b32 v225, v188, v231, v230
	ds_bpermute_b32 v228, v185, v50
	ds_bpermute_b32 v229, v185, v42
	ds_bpermute_b32 v230, v185, v51
	ds_bpermute_b32 v231, v185, v43
	s_waitcnt lgkmcnt(0)
	v_bfi_b32 v226, v188, v229, v228
	v_bfi_b32 v227, v188, v231, v230
	v_lshl_add_u64 v[178:179], v[168:169], 0, v[160:161]
	ds_bpermute_b32 v174, v184, v178
	ds_bpermute_b32 v175, v184, v179
	ds_bpermute_b32 v176, v185, v178
	ds_bpermute_b32 v177, v185, v179
	s_waitcnt lgkmcnt(0)
	v_lshl_add_u64 v[174:175], v[174:175], 0, v[186:187]
	v_lshl_add_u64 v[176:177], v[176:177], 0, v[186:187]
	global_load_dwordx4 v[48:51], v[174:175], off
	global_load_dwordx4 v[40:43], v[176:177], off
	s_waitcnt vmcnt(8)
	v_pk_fma_f32 v[62:63], v[222:223], v[192:193], v[62:63]
	v_pk_fma_f32 v[60:61], v[220:221], v[190:191], v[60:61]
	v_pk_fma_f32 v[58:59], v[226:227], v[192:193], v[58:59]
	v_pk_fma_f32 v[56:57], v[224:225], v[190:191], v[56:57]
	global_store_dwordx4 v[180:181], v[60:63], off
	global_store_dwordx4 v[198:199], v[56:59], off
	ds_bpermute_b32 v228, v184, v36
	ds_bpermute_b32 v229, v184, v32
	ds_bpermute_b32 v230, v184, v37
	ds_bpermute_b32 v231, v184, v33
	s_waitcnt lgkmcnt(0)
	v_bfi_b32 v220, v188, v229, v228
	v_bfi_b32 v221, v188, v231, v230
	ds_bpermute_b32 v228, v184, v38
	ds_bpermute_b32 v229, v184, v34
	ds_bpermute_b32 v230, v184, v39
	ds_bpermute_b32 v231, v184, v35
	s_waitcnt lgkmcnt(0)
	v_bfi_b32 v222, v188, v229, v228
	v_bfi_b32 v223, v188, v231, v230
	ds_bpermute_b32 v228, v185, v36
	ds_bpermute_b32 v229, v185, v32
	ds_bpermute_b32 v230, v185, v37
	ds_bpermute_b32 v231, v185, v33
	s_waitcnt lgkmcnt(0)
	v_bfi_b32 v224, v188, v229, v228
	v_bfi_b32 v225, v188, v231, v230
	ds_bpermute_b32 v228, v185, v38
	ds_bpermute_b32 v229, v185, v34
	ds_bpermute_b32 v230, v185, v39
	ds_bpermute_b32 v231, v185, v35
	s_waitcnt lgkmcnt(0)
	v_bfi_b32 v226, v188, v229, v228
	v_bfi_b32 v227, v188, v231, v230
	global_load_dwordx4 v[36:39], v[174:175], off offset:512
	global_load_dwordx4 v[32:35], v[176:177], off offset:512
	s_waitcnt vmcnt(8)
	v_pk_fma_f32 v[54:55], v[222:223], v[196:197], v[54:55]
	v_pk_fma_f32 v[52:53], v[220:221], v[194:195], v[52:53]
	v_pk_fma_f32 v[46:47], v[226:227], v[196:197], v[46:47]
	v_pk_fma_f32 v[44:45], v[224:225], v[194:195], v[44:45]
	global_store_dwordx4 v[180:181], v[52:55], off offset:512
	global_store_dwordx4 v[198:199], v[44:47], off offset:512
	ds_bpermute_b32 v228, v184, v28
	ds_bpermute_b32 v229, v184, v24
	ds_bpermute_b32 v230, v184, v29
	ds_bpermute_b32 v231, v184, v25
	s_waitcnt lgkmcnt(0)
	v_bfi_b32 v220, v188, v229, v228
	v_bfi_b32 v221, v188, v231, v230
	ds_bpermute_b32 v228, v184, v30
	ds_bpermute_b32 v229, v184, v26
	ds_bpermute_b32 v230, v184, v31
	ds_bpermute_b32 v231, v184, v27
	s_waitcnt lgkmcnt(0)
	v_bfi_b32 v222, v188, v229, v228
	v_bfi_b32 v223, v188, v231, v230
	ds_bpermute_b32 v228, v185, v28
	ds_bpermute_b32 v229, v185, v24
	ds_bpermute_b32 v230, v185, v29
	ds_bpermute_b32 v231, v185, v25
	s_waitcnt lgkmcnt(0)
	v_bfi_b32 v224, v188, v229, v228
	v_bfi_b32 v225, v188, v231, v230
	ds_bpermute_b32 v228, v185, v30
	ds_bpermute_b32 v229, v185, v26
	ds_bpermute_b32 v230, v185, v31
	ds_bpermute_b32 v231, v185, v27
	s_waitcnt lgkmcnt(0)
; #define PG8_BAR __builtin_amdgcn_s_barrier()
; template <class Epi, class Sched, bool ALIGN_EPI = false, bool SP2 = false>
; __device__ __forceinline__ void gemm_phase(PG8_LAS unsigned char* lds, const Gemm g, const Sched& S, const Epi& E) {
;     ...
;         if (!has_next) break;
; #pragma unroll
;         for (int a = 0; a < 2; ++a)
; #pragma unroll
;             for (int b = 0; b < 2; ++b)
; #pragma unroll
;                 for (int m = 0; m < 4; ++m)
; #pragma unroll
;                     for (int n = 0; n < 2; ++n) acc[a][b][m][n] = (f32x4){0.f, 0.f, 0.f, 0.f};
;         cur = nxt; cA = nA; cB = nB; ++ui;
;         if constexpr (ALIGN_EPI) { if (wr == 1) PG8_BAR; }
;     __device__ __forceinline__ void operator()(const pg8::f32x4 (&acc)[2][2][4][2], const pg8::Unit& u, int wr, int wc, int fr, int fq) const {
;     ...
;         for (int ai = 0; ai < 2; ++ai)
; #pragma unroll
;             for (int m = 0; m < 4; ++m) {
;                 float* rowp = base + (size_t)(ai * 128 + wr * 64 + m * 16 + fr) * DM + col0;
; #pragma unroll
;                 for (int bj = 0; bj < 2; ++bj)
; #pragma unroll
;                     for (int n = 0; n < 2; ++n) {
;                         pg8::f32x4* p = (pg8::f32x4*)(rowp + bj * 128 + n * 16);
;                         pg8::f32x4 xv = *p; xv = xv + gv[bj][n] * acc[ai][bj][m][n]; *p = xv;
;                     }
;                 if (m & 1) asm volatile("" ::: "memory");
	v_bfi_b32 v226, v188, v229, v228
	v_bfi_b32 v227, v188, v231, v230
	v_lshl_add_u64 v[178:179], v[168:169], 0, v[162:163]
	ds_bpermute_b32 v180, v184, v178
	ds_bpermute_b32 v181, v184, v179
	ds_bpermute_b32 v198, v185, v178
	ds_bpermute_b32 v199, v185, v179
	s_waitcnt lgkmcnt(0)
	v_lshl_add_u64 v[180:181], v[180:181], 0, v[186:187]
	v_lshl_add_u64 v[198:199], v[198:199], 0, v[186:187]
	global_load_dwordx4 v[28:31], v[180:181], off
	global_load_dwordx4 v[24:27], v[198:199], off
	s_waitcnt vmcnt(8)
	v_pk_fma_f32 v[50:51], v[222:223], v[192:193], v[50:51]
	v_pk_fma_f32 v[48:49], v[220:221], v[190:191], v[48:49]
	v_pk_fma_f32 v[42:43], v[226:227], v[192:193], v[42:43]
	v_pk_fma_f32 v[40:41], v[224:225], v[190:191], v[40:41]
	global_store_dwordx4 v[174:175], v[48:51], off
	global_store_dwordx4 v[176:177], v[40:43], off
	ds_bpermute_b32 v228, v184, v20
	ds_bpermute_b32 v229, v184, v12
	ds_bpermute_b32 v230, v184, v21
	ds_bpermute_b32 v231, v184, v13
	s_waitcnt lgkmcnt(0)
	v_bfi_b32 v220, v188, v229, v228
	v_bfi_b32 v221, v188, v231, v230
	ds_bpermute_b32 v228, v184, v22
	ds_bpermute_b32 v229, v184, v14
	ds_bpermute_b32 v230, v184, v23
	ds_bpermute_b32 v231, v184, v15
	s_waitcnt lgkmcnt(0)
	v_bfi_b32 v222, v188, v229, v228
	v_bfi_b32 v223, v188, v231, v230
	ds_bpermute_b32 v228, v185, v20
	ds_bpermute_b32 v229, v185, v12
	ds_bpermute_b32 v230, v185, v21
	ds_bpermute_b32 v231, v185, v13
	s_waitcnt lgkmcnt(0)
	v_bfi_b32 v224, v188, v229, v228
	v_bfi_b32 v225, v188, v231, v230
	ds_bpermute_b32 v228, v185, v22
	ds_bpermute_b32 v229, v185, v14
	ds_bpermute_b32 v230, v185, v23
	ds_bpermute_b32 v231, v185, v15
	s_waitcnt lgkmcnt(0)
	v_bfi_b32 v226, v188, v229, v228
	v_bfi_b32 v227, v188, v231, v230
	global_load_dwordx4 v[20:23], v[180:181], off offset:512
	global_load_dwordx4 v[12:15], v[198:199], off offset:512
	s_waitcnt vmcnt(8)
	v_pk_fma_f32 v[38:39], v[222:223], v[196:197], v[38:39]
	v_pk_fma_f32 v[36:37], v[220:221], v[194:195], v[36:37]
	v_pk_fma_f32 v[34:35], v[226:227], v[196:197], v[34:35]
	v_pk_fma_f32 v[32:33], v[224:225], v[194:195], v[32:33]
	global_store_dwordx4 v[174:175], v[36:39], off offset:512
	global_store_dwordx4 v[176:177], v[32:35], off offset:512
	ds_bpermute_b32 v228, v184, v16
	ds_bpermute_b32 v229, v184, v8
	ds_bpermute_b32 v230, v184, v17
	ds_bpermute_b32 v231, v184, v9
	s_waitcnt lgkmcnt(0)
	v_bfi_b32 v220, v188, v229, v228
	v_bfi_b32 v221, v188, v231, v230
	ds_bpermute_b32 v228, v184, v18
	ds_bpermute_b32 v229, v184, v10
	ds_bpermute_b32 v230, v184, v19
	ds_bpermute_b32 v231, v184, v11
	s_waitcnt lgkmcnt(0)
	v_bfi_b32 v222, v188, v229, v228
	v_bfi_b32 v223, v188, v231, v230
	ds_bpermute_b32 v228, v185, v16
	ds_bpermute_b32 v229, v185, v8
	ds_bpermute_b32 v230, v185, v17
	ds_bpermute_b32 v231, v185, v9
	s_waitcnt lgkmcnt(0)
	v_bfi_b32 v224, v188, v229, v228
	v_bfi_b32 v225, v188, v231, v230
	ds_bpermute_b32 v228, v185, v18
	ds_bpermute_b32 v229, v185, v10
	ds_bpermute_b32 v230, v185, v19
	ds_bpermute_b32 v231, v185, v11
	s_waitcnt lgkmcnt(0)
	v_bfi_b32 v226, v188, v229, v228
	v_bfi_b32 v227, v188, v231, v230
	s_waitcnt vmcnt(6)
	v_pk_fma_f32 v[30:31], v[222:223], v[192:193], v[30:31]
	v_pk_fma_f32 v[28:29], v[220:221], v[190:191], v[28:29]
	v_pk_fma_f32 v[26:27], v[226:227], v[192:193], v[26:27]
	v_pk_fma_f32 v[24:25], v[224:225], v[190:191], v[24:25]
	global_store_dwordx4 v[180:181], v[28:31], off
	global_store_dwordx4 v[198:199], v[24:27], off
	ds_bpermute_b32 v228, v184, v4
	ds_bpermute_b32 v229, v184, v0
	ds_bpermute_b32 v230, v184, v5
	ds_bpermute_b32 v231, v184, v1
	s_waitcnt lgkmcnt(0)
	v_bfi_b32 v220, v188, v229, v228
	v_bfi_b32 v221, v188, v231, v230
	ds_bpermute_b32 v228, v184, v6
	ds_bpermute_b32 v229, v184, v2
	ds_bpermute_b32 v230, v184, v7
	ds_bpermute_b32 v231, v184, v3
	s_waitcnt lgkmcnt(0)
	v_bfi_b32 v222, v188, v229, v228
	v_bfi_b32 v223, v188, v231, v230
	ds_bpermute_b32 v228, v185, v4
	ds_bpermute_b32 v229, v185, v0
	ds_bpermute_b32 v230, v185, v5
	ds_bpermute_b32 v231, v185, v1
	s_waitcnt lgkmcnt(0)
	v_bfi_b32 v224, v188, v229, v228
	v_bfi_b32 v225, v188, v231, v230
	ds_bpermute_b32 v228, v185, v6
	ds_bpermute_b32 v229, v185, v2
	ds_bpermute_b32 v230, v185, v7
	ds_bpermute_b32 v231, v185, v3
	s_waitcnt lgkmcnt(0)
	v_bfi_b32 v226, v188, v229, v228
	v_bfi_b32 v227, v188, v231, v230
	s_waitcnt vmcnt(4)
	v_pk_fma_f32 v[22:23], v[222:223], v[196:197], v[22:23]
	v_pk_fma_f32 v[20:21], v[220:221], v[194:195], v[20:21]
	v_pk_fma_f32 v[14:15], v[226:227], v[196:197], v[14:15]
	v_pk_fma_f32 v[12:13], v[224:225], v[194:195], v[12:13]
	global_store_dwordx4 v[180:181], v[20:23], off offset:512
	global_store_dwordx4 v[198:199], v[12:15], off offset:512
	s_cbranch_vccnz .LBB0_866
	s_andn2_b64 vcc, exec, s[10:11]
	s_cbranch_vccnz .LBB0_865
	s_barrier
	s_branch .LBB0_865

;     __device__ __forceinline__ void operator()(const pg8::f32x4 (&acc)[2][2][4][2], const pg8::Unit& u, int wr, int wc, int fr, int fq) const {
;         const int b = u.pm / 9, j = u.pm - b * 9;
;         float* base = (j == 0) ? xc + (size_t)b * CTX * DM : out + ((size_t)b * SEQ + (size_t)(j - 1) * 256) * DM;
;         const float* g = gate + (size_t)((j == 0) ? 16 : b) * MODW;
;         const int col0 = u.pn * 256 + wc * 32 + 4 * fq;
;         pg8::f32x4 gv[2][2];
; #pragma unroll
;         for (int bj = 0; bj < 2; ++bj)
; #pragma unroll
;             for (int n = 0; n < 2; ++n) gv[bj][n] = *(const pg8::f32x4*)(g + col0 + bj * 128 + n * 16);
; #pragma unroll
;         for (int ai = 0; ai < 2; ++ai)
; #pragma unroll
;             for (int m = 0; m < 4; ++m) {
;                 float* rowp = base + (size_t)(ai * 128 + wr * 64 + m * 16 + fr) * DM + col0;
; #pragma unroll
;                 for (int bj = 0; bj < 2; ++bj)
; #pragma unroll
;                     for (int n = 0; n < 2; ++n) {
;                         pg8::f32x4* p = (pg8::f32x4*)(rowp + bj * 128 + n * 16);
;                         pg8::f32x4 xv = *p; xv = xv + gv[bj][n] * acc[ai][bj][m][n]; *p = xv;
;                     }
.LBB0_1099:
	s_lshl_b64 s[12:13], s[58:59], 2
	v_lshl_or_b32 v88, s62, 8, v171
	s_add_u32 s12, s11, s12
	v_ashrrev_i32_e32 v89, 31, v88
	s_addc_u32 s13, s24, s13
	v_lshlrev_b64 v[168:169], 2, v[88:89]
	v_lshl_add_u64 v[88:89], s[12:13], 0, v[168:169]
	v_lshl_add_u64 v[168:169], s[50:51], 0, v[168:169]
	v_lshl_add_u64 v[178:179], v[168:169], 0, v[148:149]
	global_load_dwordx4 v[108:111], v[88:89], off
	global_load_dwordx4 v[104:107], v[88:89], off offset:64
	global_load_dwordx4 v[100:103], v[88:89], off offset:512
	s_nop 0
	global_load_dwordx4 v[88:91], v[88:89], off offset:576
	s_mov_b64 s[50:51], -1
	s_and_b64 vcc, exec, s[40:41]
	s_waitcnt vmcnt(0)
	v_and_b32_e32 v228, 63, v200
	v_lshrrev_b32_e32 v229, 3, v228
	v_and_b32_e32 v184, 3, v228
	v_lshl_or_b32 v184, v184, 4, v229
	v_lshlrev_b32_e32 v184, 2, v184
	v_add_u32_e32 v185, 32, v184
	v_bfe_u32 v229, v228, 2, 1
	v_lshlrev_b32_e32 v186, 6, v229
	v_mov_b32_e32 v187, 0
	v_sub_u32_e32 v188, 0, v229
	ds_bpermute_b32 v228, v184, v108
	ds_bpermute_b32 v229, v184, v104
	s_waitcnt lgkmcnt(0)
	v_bfi_b32 v190, v188, v229, v228
	ds_bpermute_b32 v228, v184, v109
	ds_bpermute_b32 v229, v184, v105
	s_waitcnt lgkmcnt(0)
	v_bfi_b32 v191, v188, v229, v228
	ds_bpermute_b32 v228, v184, v110
	ds_bpermute_b32 v229, v184, v106
	s_waitcnt lgkmcnt(0)
	v_bfi_b32 v192, v188, v229, v228
	ds_bpermute_b32 v228, v184, v111
	ds_bpermute_b32 v229, v184, v107
	s_waitcnt lgkmcnt(0)
	v_bfi_b32 v193, v188, v229, v228
	ds_bpermute_b32 v228, v184, v100
	ds_bpermute_b32 v229, v184, v88
	s_waitcnt lgkmcnt(0)
	v_bfi_b32 v194, v188, v229, v228
	ds_bpermute_b32 v228, v184, v101
	ds_bpermute_b32 v229, v184, v89
	s_waitcnt lgkmcnt(0)
	v_bfi_b32 v195, v188, v229, v228
	ds_bpermute_b32 v228, v184, v102
	ds_bpermute_b32 v229, v184, v90
	s_waitcnt lgkmcnt(0)
	v_bfi_b32 v196, v188, v229, v228
	ds_bpermute_b32 v228, v184, v103
	ds_bpermute_b32 v229, v184, v91
	s_waitcnt lgkmcnt(0)
	v_bfi_b32 v197, v188, v229, v228
	v_lshl_add_u64 v[178:179], v[168:169], 0, v[148:149]
	ds_bpermute_b32 v174, v184, v178
	ds_bpermute_b32 v175, v184, v179
	ds_bpermute_b32 v176, v185, v178
	ds_bpermute_b32 v177, v185, v179
	s_waitcnt lgkmcnt(0)
	v_lshl_add_u64 v[174:175], v[174:175], 0, v[186:187]
	v_lshl_add_u64 v[176:177], v[176:177], 0, v[186:187]
	global_load_dwordx4 v[204:207], v[174:175], off
	global_load_dwordx4 v[208:211], v[176:177], off
	global_load_dwordx4 v[212:215], v[174:175], off offset:512
	global_load_dwordx4 v[216:219], v[176:177], off offset:512
	ds_bpermute_b32 v228, v184, v142
	ds_bpermute_b32 v229, v184, v138
	ds_bpermute_b32 v230, v184, v143
	ds_bpermute_b32 v231, v184, v139
	s_waitcnt lgkmcnt(0)
	v_bfi_b32 v220, v188, v229, v228
	v_bfi_b32 v221, v188, v231, v230
	ds_bpermute_b32 v228, v184, v144
	ds_bpermute_b32 v229, v184, v140
	ds_bpermute_b32 v230, v184, v145
	ds_bpermute_b32 v231, v184, v141
	s_waitcnt lgkmcnt(0)
	v_bfi_b32 v222, v188, v229, v228
	v_bfi_b32 v223, v188, v231, v230
	ds_bpermute_b32 v228, v185, v142
	ds_bpermute_b32 v229, v185, v138
	ds_bpermute_b32 v230, v185, v143
	ds_bpermute_b32 v231, v185, v139
	s_waitcnt lgkmcnt(0)
	v_bfi_b32 v224, v188, v229, v228
	v_bfi_b32 v225, v188, v231, v230
	ds_bpermute_b32 v228, v185, v144
	ds_bpermute_b32 v229, v185, v140
	ds_bpermute_b32 v230, v185, v145
	ds_bpermute_b32 v231, v185, v141
	s_waitcnt lgkmcnt(0)
	v_bfi_b32 v226, v188, v229, v228
	v_bfi_b32 v227, v188, v231, v230
	v_lshl_add_u64 v[178:179], v[168:169], 0, v[150:151]
	ds_bpermute_b32 v180, v184, v178
	ds_bpermute_b32 v181, v184, v179
	ds_bpermute_b32 v198, v185, v178
	ds_bpermute_b32 v199, v185, v179
	s_waitcnt lgkmcnt(0)
	v_lshl_add_u64 v[180:181], v[180:181], 0, v[186:187]
	v_lshl_add_u64 v[198:199], v[198:199], 0, v[186:187]
	global_load_dwordx4 v[142:145], v[180:181], off
	global_load_dwordx4 v[138:141], v[198:199], off
	s_waitcnt vmcnt(4)
	v_pk_fma_f32 v[206:207], v[222:223], v[192:193], v[206:207]
	v_pk_fma_f32 v[204:205], v[220:221], v[190:191], v[204:205]
	v_pk_fma_f32 v[210:211], v[226:227], v[192:193], v[210:211]
	v_pk_fma_f32 v[208:209], v[224:225], v[190:191], v[208:209]
	global_store_dwordx4 v[174:175], v[204:207], off
	global_store_dwordx4 v[176:177], v[208:211], off
	ds_bpermute_b32 v228, v184, v134
	ds_bpermute_b32 v229, v184, v124
	ds_bpermute_b32 v230, v184, v135
	ds_bpermute_b32 v231, v184, v125
	s_waitcnt lgkmcnt(0)
	v_bfi_b32 v220, v188, v229, v228
	v_bfi_b32 v221, v188, v231, v230
	ds_bpermute_b32 v228, v184, v136
	ds_bpermute_b32 v229, v184, v126
	ds_bpermute_b32 v230, v184, v137
	ds_bpermute_b32 v231, v184, v127
	s_waitcnt lgkmcnt(0)
	v_bfi_b32 v222, v188, v229, v228
	v_bfi_b32 v223, v188, v231, v230
	ds_bpermute_b32 v228, v185, v134
	ds_bpermute_b32 v229, v185, v124
	ds_bpermute_b32 v230, v185, v135
	ds_bpermute_b32 v231, v185, v125
	s_waitcnt lgkmcnt(0)
	v_bfi_b32 v224, v188, v229, v228
	v_bfi_b32 v225, v188, v231, v230
	ds_bpermute_b32 v228, v185, v136
	ds_bpermute_b32 v229, v185, v126
	ds_bpermute_b32 v230, v185, v137
	ds_bpermute_b32 v231, v185, v127
	s_waitcnt lgkmcnt(0)
	v_bfi_b32 v226, v188, v229, v228
	v_bfi_b32 v227, v188, v231, v230
	global_load_dwordx4 v[134:137], v[180:181], off offset:512
	global_load_dwordx4 v[124:127], v[198:199], off offset:512
	s_waitcnt vmcnt(6)
	v_pk_fma_f32 v[214:215], v[222:223], v[196:197], v[214:215]
	v_pk_fma_f32 v[212:213], v[220:221], v[194:195], v[212:213]
	v_pk_fma_f32 v[218:219], v[226:227], v[196:197], v[218:219]
	v_pk_fma_f32 v[216:217], v[224:225], v[194:195], v[216:217]
	global_store_dwordx4 v[174:175], v[212:215], off offset:512
	global_store_dwordx4 v[176:177], v[216:219], off offset:512
	ds_bpermute_b32 v228, v184, v130
	ds_bpermute_b32 v229, v184, v120
	ds_bpermute_b32 v230, v184, v131
	ds_bpermute_b32 v231, v184, v121
	s_waitcnt lgkmcnt(0)
;     __device__ __forceinline__ void operator()(const pg8::f32x4 (&acc)[2][2][4][2], const pg8::Unit& u, int wr, int wc, int fr, int fq) const {
;     ...
;         for (int ai = 0; ai < 2; ++ai)
; #pragma unroll
;             for (int m = 0; m < 4; ++m) {
;                 float* rowp = base + (size_t)(ai * 128 + wr * 64 + m * 16 + fr) * DM + col0;
; #pragma unroll
;                 for (int bj = 0; bj < 2; ++bj)
; #pragma unroll
;                     for (int n = 0; n < 2; ++n) {
;                         pg8::f32x4* p = (pg8::f32x4*)(rowp + bj * 128 + n * 16);
;                         pg8::f32x4 xv = *p; xv = xv + gv[bj][n] * acc[ai][bj][m][n]; *p = xv;
;                     }
	v_bfi_b32 v220, v188, v229, v228
	v_bfi_b32 v221, v188, v231, v230
	ds_bpermute_b32 v228, v184, v132
	ds_bpermute_b32 v229, v184, v122
	ds_bpermute_b32 v230, v184, v133
	ds_bpermute_b32 v231, v184, v123
	s_waitcnt lgkmcnt(0)
	v_bfi_b32 v222, v188, v229, v228
	v_bfi_b32 v223, v188, v231, v230
	ds_bpermute_b32 v228, v185, v130
	ds_bpermute_b32 v229, v185, v120
	ds_bpermute_b32 v230, v185, v131
	ds_bpermute_b32 v231, v185, v121
	s_waitcnt lgkmcnt(0)
	v_bfi_b32 v224, v188, v229, v228
	v_bfi_b32 v225, v188, v231, v230
	ds_bpermute_b32 v228, v185, v132
	ds_bpermute_b32 v229, v185, v122
	ds_bpermute_b32 v230, v185, v133
	ds_bpermute_b32 v231, v185, v123
	s_waitcnt lgkmcnt(0)
	v_bfi_b32 v226, v188, v229, v228
	v_bfi_b32 v227, v188, v231, v230
	v_lshl_add_u64 v[178:179], v[168:169], 0, v[152:153]
	ds_bpermute_b32 v174, v184, v178
	ds_bpermute_b32 v175, v184, v179
	ds_bpermute_b32 v176, v185, v178
	ds_bpermute_b32 v177, v185, v179
	s_waitcnt lgkmcnt(0)
	v_lshl_add_u64 v[174:175], v[174:175], 0, v[186:187]
	v_lshl_add_u64 v[176:177], v[176:177], 0, v[186:187]
	global_load_dwordx4 v[130:133], v[174:175], off
	global_load_dwordx4 v[120:123], v[176:177], off
	s_waitcnt vmcnt(8)
	v_pk_fma_f32 v[144:145], v[222:223], v[192:193], v[144:145]
	v_pk_fma_f32 v[142:143], v[220:221], v[190:191], v[142:143]
	v_pk_fma_f32 v[140:141], v[226:227], v[192:193], v[140:141]
	v_pk_fma_f32 v[138:139], v[224:225], v[190:191], v[138:139]
	global_store_dwordx4 v[180:181], v[142:145], off
	global_store_dwordx4 v[198:199], v[138:141], off
	ds_bpermute_b32 v228, v184, v116
	ds_bpermute_b32 v229, v184, v112
	ds_bpermute_b32 v230, v184, v117
	ds_bpermute_b32 v231, v184, v113
	s_waitcnt lgkmcnt(0)
	v_bfi_b32 v220, v188, v229, v228
	v_bfi_b32 v221, v188, v231, v230
	ds_bpermute_b32 v228, v184, v118
	ds_bpermute_b32 v229, v184, v114
	ds_bpermute_b32 v230, v184, v119
	ds_bpermute_b32 v231, v184, v115
	s_waitcnt lgkmcnt(0)
	v_bfi_b32 v222, v188, v229, v228
	v_bfi_b32 v223, v188, v231, v230
	ds_bpermute_b32 v228, v185, v116
	ds_bpermute_b32 v229, v185, v112
	ds_bpermute_b32 v230, v185, v117
	ds_bpermute_b32 v231, v185, v113
	s_waitcnt lgkmcnt(0)
	v_bfi_b32 v224, v188, v229, v228
	v_bfi_b32 v225, v188, v231, v230
	ds_bpermute_b32 v228, v185, v118
	ds_bpermute_b32 v229, v185, v114
	ds_bpermute_b32 v230, v185, v119
	ds_bpermute_b32 v231, v185, v115
	s_waitcnt lgkmcnt(0)
	v_bfi_b32 v226, v188, v229, v228
	v_bfi_b32 v227, v188, v231, v230
	global_load_dwordx4 v[116:119], v[174:175], off offset:512
	global_load_dwordx4 v[112:115], v[176:177], off offset:512
	s_waitcnt vmcnt(8)
	v_pk_fma_f32 v[136:137], v[222:223], v[196:197], v[136:137]
	v_pk_fma_f32 v[134:135], v[220:221], v[194:195], v[134:135]
	v_pk_fma_f32 v[126:127], v[226:227], v[196:197], v[126:127]
	v_pk_fma_f32 v[124:125], v[224:225], v[194:195], v[124:125]
	global_store_dwordx4 v[180:181], v[134:137], off offset:512
	global_store_dwordx4 v[198:199], v[124:127], off offset:512
	ds_bpermute_b32 v228, v184, v96
	ds_bpermute_b32 v229, v184, v92
	ds_bpermute_b32 v230, v184, v97
	ds_bpermute_b32 v231, v184, v93
	s_waitcnt lgkmcnt(0)
	v_bfi_b32 v220, v188, v229, v228
	v_bfi_b32 v221, v188, v231, v230
	ds_bpermute_b32 v228, v184, v98
	ds_bpermute_b32 v229, v184, v94
	ds_bpermute_b32 v230, v184, v99
	ds_bpermute_b32 v231, v184, v95
	s_waitcnt lgkmcnt(0)
	v_bfi_b32 v222, v188, v229, v228
	v_bfi_b32 v223, v188, v231, v230
	ds_bpermute_b32 v228, v185, v96
	ds_bpermute_b32 v229, v185, v92
	ds_bpermute_b32 v230, v185, v97
	ds_bpermute_b32 v231, v185, v93
	s_waitcnt lgkmcnt(0)
	v_bfi_b32 v224, v188, v229, v228
	v_bfi_b32 v225, v188, v231, v230
	ds_bpermute_b32 v228, v185, v98
	ds_bpermute_b32 v229, v185, v94
	ds_bpermute_b32 v230, v185, v99
	ds_bpermute_b32 v231, v185, v95
	s_waitcnt lgkmcnt(0)
	v_bfi_b32 v226, v188, v229, v228
	v_bfi_b32 v227, v188, v231, v230
	v_lshl_add_u64 v[178:179], v[168:169], 0, v[154:155]
	ds_bpermute_b32 v180, v184, v178
	ds_bpermute_b32 v181, v184, v179
	ds_bpermute_b32 v198, v185, v178
	ds_bpermute_b32 v199, v185, v179
	s_waitcnt lgkmcnt(0)
	v_lshl_add_u64 v[180:181], v[180:181], 0, v[186:187]
	v_lshl_add_u64 v[198:199], v[198:199], 0, v[186:187]
	global_load_dwordx4 v[96:99], v[180:181], off
	global_load_dwordx4 v[92:95], v[198:199], off
	s_waitcnt vmcnt(8)
	v_pk_fma_f32 v[132:133], v[222:223], v[192:193], v[132:133]
	v_pk_fma_f32 v[130:131], v[220:221], v[190:191], v[130:131]
	v_pk_fma_f32 v[122:123], v[226:227], v[192:193], v[122:123]
	v_pk_fma_f32 v[120:121], v[224:225], v[190:191], v[120:121]
	global_store_dwordx4 v[174:175], v[130:133], off
	global_store_dwordx4 v[176:177], v[120:123], off
	ds_bpermute_b32 v228, v184, v84
	ds_bpermute_b32 v229, v184, v76
	ds_bpermute_b32 v230, v184, v85
	ds_bpermute_b32 v231, v184, v77
	s_waitcnt lgkmcnt(0)
	v_bfi_b32 v220, v188, v229, v228
	v_bfi_b32 v221, v188, v231, v230
	ds_bpermute_b32 v228, v184, v86
	ds_bpermute_b32 v229, v184, v78
	ds_bpermute_b32 v230, v184, v87
	ds_bpermute_b32 v231, v184, v79
	s_waitcnt lgkmcnt(0)
	v_bfi_b32 v222, v188, v229, v228
	v_bfi_b32 v223, v188, v231, v230
	ds_bpermute_b32 v228, v185, v84
	ds_bpermute_b32 v229, v185, v76
	ds_bpermute_b32 v230, v185, v85
	ds_bpermute_b32 v231, v185, v77
	s_waitcnt lgkmcnt(0)
	v_bfi_b32 v224, v188, v229, v228
	v_bfi_b32 v225, v188, v231, v230
	ds_bpermute_b32 v228, v185, v86
	ds_bpermute_b32 v229, v185, v78
	ds_bpermute_b32 v230, v185, v87
	ds_bpermute_b32 v231, v185, v79
	s_waitcnt lgkmcnt(0)
	v_bfi_b32 v226, v188, v229, v228
	v_bfi_b32 v227, v188, v231, v230
	global_load_dwordx4 v[84:87], v[180:181], off offset:512
	global_load_dwordx4 v[76:79], v[198:199], off offset:512
	s_waitcnt vmcnt(8)
;     __device__ __forceinline__ void operator()(const pg8::f32x4 (&acc)[2][2][4][2], const pg8::Unit& u, int wr, int wc, int fr, int fq) const {
;     ...
;         for (int ai = 0; ai < 2; ++ai)
; #pragma unroll
;             for (int m = 0; m < 4; ++m) {
;                 float* rowp = base + (size_t)(ai * 128 + wr * 64 + m * 16 + fr) * DM + col0;
; #pragma unroll
;                 for (int bj = 0; bj < 2; ++bj)
; #pragma unroll
;                     for (int n = 0; n < 2; ++n) {
;                         pg8::f32x4* p = (pg8::f32x4*)(rowp + bj * 128 + n * 16);
;                         pg8::f32x4 xv = *p; xv = xv + gv[bj][n] * acc[ai][bj][m][n]; *p = xv;
;                     }
	v_pk_fma_f32 v[118:119], v[222:223], v[196:197], v[118:119]
	v_pk_fma_f32 v[116:117], v[220:221], v[194:195], v[116:117]
	v_pk_fma_f32 v[114:115], v[226:227], v[196:197], v[114:115]
	v_pk_fma_f32 v[112:113], v[224:225], v[194:195], v[112:113]
	global_store_dwordx4 v[174:175], v[116:119], off offset:512
	global_store_dwordx4 v[176:177], v[112:115], off offset:512
	ds_bpermute_b32 v228, v184, v80
	ds_bpermute_b32 v229, v184, v72
	ds_bpermute_b32 v230, v184, v81
	ds_bpermute_b32 v231, v184, v73
	s_waitcnt lgkmcnt(0)
	v_bfi_b32 v220, v188, v229, v228
	v_bfi_b32 v221, v188, v231, v230
	ds_bpermute_b32 v228, v184, v82
	ds_bpermute_b32 v229, v184, v74
	ds_bpermute_b32 v230, v184, v83
	ds_bpermute_b32 v231, v184, v75
	s_waitcnt lgkmcnt(0)
	v_bfi_b32 v222, v188, v229, v228
	v_bfi_b32 v223, v188, v231, v230
	ds_bpermute_b32 v228, v185, v80
	ds_bpermute_b32 v229, v185, v72
	ds_bpermute_b32 v230, v185, v81
	ds_bpermute_b32 v231, v185, v73
	s_waitcnt lgkmcnt(0)
	v_bfi_b32 v224, v188, v229, v228
	v_bfi_b32 v225, v188, v231, v230
	ds_bpermute_b32 v228, v185, v82
	ds_bpermute_b32 v229, v185, v74
	ds_bpermute_b32 v230, v185, v83
	ds_bpermute_b32 v231, v185, v75
	s_waitcnt lgkmcnt(0)
	v_bfi_b32 v226, v188, v229, v228
	v_bfi_b32 v227, v188, v231, v230
	v_lshl_add_u64 v[178:179], v[168:169], 0, v[156:157]
	ds_bpermute_b32 v174, v184, v178
	ds_bpermute_b32 v175, v184, v179
	ds_bpermute_b32 v176, v185, v178
	ds_bpermute_b32 v177, v185, v179
	s_waitcnt lgkmcnt(0)
	v_lshl_add_u64 v[174:175], v[174:175], 0, v[186:187]
	v_lshl_add_u64 v[176:177], v[176:177], 0, v[186:187]
	global_load_dwordx4 v[80:83], v[174:175], off
	global_load_dwordx4 v[72:75], v[176:177], off
	s_waitcnt vmcnt(8)
	v_pk_fma_f32 v[98:99], v[222:223], v[192:193], v[98:99]
	v_pk_fma_f32 v[96:97], v[220:221], v[190:191], v[96:97]
	v_pk_fma_f32 v[94:95], v[226:227], v[192:193], v[94:95]
	v_pk_fma_f32 v[92:93], v[224:225], v[190:191], v[92:93]
	global_store_dwordx4 v[180:181], v[96:99], off
	global_store_dwordx4 v[198:199], v[92:95], off
	ds_bpermute_b32 v228, v184, v68
	ds_bpermute_b32 v229, v184, v64
	ds_bpermute_b32 v230, v184, v69
	ds_bpermute_b32 v231, v184, v65
	s_waitcnt lgkmcnt(0)
	v_bfi_b32 v220, v188, v229, v228
	v_bfi_b32 v221, v188, v231, v230
	ds_bpermute_b32 v228, v184, v70
	ds_bpermute_b32 v229, v184, v66
	ds_bpermute_b32 v230, v184, v71
	ds_bpermute_b32 v231, v184, v67
	s_waitcnt lgkmcnt(0)
	v_bfi_b32 v222, v188, v229, v228
	v_bfi_b32 v223, v188, v231, v230
	ds_bpermute_b32 v228, v185, v68
	ds_bpermute_b32 v229, v185, v64
	ds_bpermute_b32 v230, v185, v69
	ds_bpermute_b32 v231, v185, v65
	s_waitcnt lgkmcnt(0)
	v_bfi_b32 v224, v188, v229, v228
	v_bfi_b32 v225, v188, v231, v230
	ds_bpermute_b32 v228, v185, v70
	ds_bpermute_b32 v229, v185, v66
	ds_bpermute_b32 v230, v185, v71
	ds_bpermute_b32 v231, v185, v67
	s_waitcnt lgkmcnt(0)
	v_bfi_b32 v226, v188, v229, v228
	v_bfi_b32 v227, v188, v231, v230
	global_load_dwordx4 v[68:71], v[174:175], off offset:512
	global_load_dwordx4 v[64:67], v[176:177], off offset:512
	s_waitcnt vmcnt(8)
	v_pk_fma_f32 v[86:87], v[222:223], v[196:197], v[86:87]
	v_pk_fma_f32 v[84:85], v[220:221], v[194:195], v[84:85]
	v_pk_fma_f32 v[78:79], v[226:227], v[196:197], v[78:79]
	v_pk_fma_f32 v[76:77], v[224:225], v[194:195], v[76:77]
	global_store_dwordx4 v[180:181], v[84:87], off offset:512
	global_store_dwordx4 v[198:199], v[76:79], off offset:512
	ds_bpermute_b32 v228, v184, v60
	ds_bpermute_b32 v229, v184, v56
	ds_bpermute_b32 v230, v184, v61
	ds_bpermute_b32 v231, v184, v57
	s_waitcnt lgkmcnt(0)
	v_bfi_b32 v220, v188, v229, v228
	v_bfi_b32 v221, v188, v231, v230
	ds_bpermute_b32 v228, v184, v62
	ds_bpermute_b32 v229, v184, v58
	ds_bpermute_b32 v230, v184, v63
	ds_bpermute_b32 v231, v184, v59
	s_waitcnt lgkmcnt(0)
	v_bfi_b32 v222, v188, v229, v228
	v_bfi_b32 v223, v188, v231, v230
	ds_bpermute_b32 v228, v185, v60
	ds_bpermute_b32 v229, v185, v56
	ds_bpermute_b32 v230, v185, v61
	ds_bpermute_b32 v231, v185, v57
	s_waitcnt lgkmcnt(0)
	v_bfi_b32 v224, v188, v229, v228
	v_bfi_b32 v225, v188, v231, v230
	ds_bpermute_b32 v228, v185, v62
	ds_bpermute_b32 v229, v185, v58
	ds_bpermute_b32 v230, v185, v63
	ds_bpermute_b32 v231, v185, v59
	s_waitcnt lgkmcnt(0)
	v_bfi_b32 v226, v188, v229, v228
	v_bfi_b32 v227, v188, v231, v230
	v_lshl_add_u64 v[178:179], v[168:169], 0, v[158:159]
	ds_bpermute_b32 v180, v184, v178
	ds_bpermute_b32 v181, v184, v179
	ds_bpermute_b32 v198, v185, v178
	ds_bpermute_b32 v199, v185, v179
	s_waitcnt lgkmcnt(0)
	v_lshl_add_u64 v[180:181], v[180:181], 0, v[186:187]
	v_lshl_add_u64 v[198:199], v[198:199], 0, v[186:187]
	global_load_dwordx4 v[60:63], v[180:181], off
	global_load_dwordx4 v[56:59], v[198:199], off
	s_waitcnt vmcnt(8)
	v_pk_fma_f32 v[82:83], v[222:223], v[192:193], v[82:83]
	v_pk_fma_f32 v[80:81], v[220:221], v[190:191], v[80:81]
	v_pk_fma_f32 v[74:75], v[226:227], v[192:193], v[74:75]
	v_pk_fma_f32 v[72:73], v[224:225], v[190:191], v[72:73]
	global_store_dwordx4 v[174:175], v[80:83], off
	global_store_dwordx4 v[176:177], v[72:75], off
	ds_bpermute_b32 v228, v184, v52
	ds_bpermute_b32 v229, v184, v44
	ds_bpermute_b32 v230, v184, v53
	ds_bpermute_b32 v231, v184, v45
	s_waitcnt lgkmcnt(0)
	v_bfi_b32 v220, v188, v229, v228
	v_bfi_b32 v221, v188, v231, v230
	ds_bpermute_b32 v228, v184, v54
	ds_bpermute_b32 v229, v184, v46
	ds_bpermute_b32 v230, v184, v55
	ds_bpermute_b32 v231, v184, v47
	s_waitcnt lgkmcnt(0)
	v_bfi_b32 v222, v188, v229, v228
	v_bfi_b32 v223, v188, v231, v230
	ds_bpermute_b32 v228, v185, v52
	ds_bpermute_b32 v229, v185, v44
	ds_bpermute_b32 v230, v185, v53
	ds_bpermute_b32 v231, v185, v45
	s_waitcnt lgkmcnt(0)
;     __device__ __forceinline__ void operator()(const pg8::f32x4 (&acc)[2][2][4][2], const pg8::Unit& u, int wr, int wc, int fr, int fq) const {
;     ...
;         for (int ai = 0; ai < 2; ++ai)
; #pragma unroll
;             for (int m = 0; m < 4; ++m) {
;                 float* rowp = base + (size_t)(ai * 128 + wr * 64 + m * 16 + fr) * DM + col0;
; #pragma unroll
;                 for (int bj = 0; bj < 2; ++bj)
; #pragma unroll
;                     for (int n = 0; n < 2; ++n) {
;                         pg8::f32x4* p = (pg8::f32x4*)(rowp + bj * 128 + n * 16);
;                         pg8::f32x4 xv = *p; xv = xv + gv[bj][n] * acc[ai][bj][m][n]; *p = xv;
;                     }
	v_bfi_b32 v224, v188, v229, v228
	v_bfi_b32 v225, v188, v231, v230
	ds_bpermute_b32 v228, v185, v54
	ds_bpermute_b32 v229, v185, v46
	ds_bpermute_b32 v230, v185, v55
	ds_bpermute_b32 v231, v185, v47
	s_waitcnt lgkmcnt(0)
	v_bfi_b32 v226, v188, v229, v228
	v_bfi_b32 v227, v188, v231, v230
	global_load_dwordx4 v[52:55], v[180:181], off offset:512
	global_load_dwordx4 v[44:47], v[198:199], off offset:512
	s_waitcnt vmcnt(8)
	v_pk_fma_f32 v[70:71], v[222:223], v[196:197], v[70:71]
	v_pk_fma_f32 v[68:69], v[220:221], v[194:195], v[68:69]
	v_pk_fma_f32 v[66:67], v[226:227], v[196:197], v[66:67]
	v_pk_fma_f32 v[64:65], v[224:225], v[194:195], v[64:65]
	global_store_dwordx4 v[174:175], v[68:71], off offset:512
	global_store_dwordx4 v[176:177], v[64:67], off offset:512
	ds_bpermute_b32 v228, v184, v48
	ds_bpermute_b32 v229, v184, v40
	ds_bpermute_b32 v230, v184, v49
	ds_bpermute_b32 v231, v184, v41
	s_waitcnt lgkmcnt(0)
	v_bfi_b32 v220, v188, v229, v228
	v_bfi_b32 v221, v188, v231, v230
	ds_bpermute_b32 v228, v184, v50
	ds_bpermute_b32 v229, v184, v42
	ds_bpermute_b32 v230, v184, v51
	ds_bpermute_b32 v231, v184, v43
	s_waitcnt lgkmcnt(0)
	v_bfi_b32 v222, v188, v229, v228
	v_bfi_b32 v223, v188, v231, v230
	ds_bpermute_b32 v228, v185, v48
	ds_bpermute_b32 v229, v185, v40
	ds_bpermute_b32 v230, v185, v49
	ds_bpermute_b32 v231, v185, v41
	s_waitcnt lgkmcnt(0)
	v_bfi_b32 v224, v188, v229, v228
	v_bfi_b32 v225, v188, v231, v230
	ds_bpermute_b32 v228, v185, v50
	ds_bpermute_b32 v229, v185, v42
	ds_bpermute_b32 v230, v185, v51
	ds_bpermute_b32 v231, v185, v43
	s_waitcnt lgkmcnt(0)
	v_bfi_b32 v226, v188, v229, v228
	v_bfi_b32 v227, v188, v231, v230
	v_lshl_add_u64 v[178:179], v[168:169], 0, v[160:161]
	ds_bpermute_b32 v174, v184, v178
	ds_bpermute_b32 v175, v184, v179
	ds_bpermute_b32 v176, v185, v178
	ds_bpermute_b32 v177, v185, v179
	s_waitcnt lgkmcnt(0)
	v_lshl_add_u64 v[174:175], v[174:175], 0, v[186:187]
	v_lshl_add_u64 v[176:177], v[176:177], 0, v[186:187]
	global_load_dwordx4 v[48:51], v[174:175], off
	global_load_dwordx4 v[40:43], v[176:177], off
	s_waitcnt vmcnt(8)
	v_pk_fma_f32 v[62:63], v[222:223], v[192:193], v[62:63]
	v_pk_fma_f32 v[60:61], v[220:221], v[190:191], v[60:61]
	v_pk_fma_f32 v[58:59], v[226:227], v[192:193], v[58:59]
	v_pk_fma_f32 v[56:57], v[224:225], v[190:191], v[56:57]
	global_store_dwordx4 v[180:181], v[60:63], off
	global_store_dwordx4 v[198:199], v[56:59], off
	ds_bpermute_b32 v228, v184, v36
	ds_bpermute_b32 v229, v184, v32
	ds_bpermute_b32 v230, v184, v37
	ds_bpermute_b32 v231, v184, v33
	s_waitcnt lgkmcnt(0)
	v_bfi_b32 v220, v188, v229, v228
	v_bfi_b32 v221, v188, v231, v230
	ds_bpermute_b32 v228, v184, v38
	ds_bpermute_b32 v229, v184, v34
	ds_bpermute_b32 v230, v184, v39
	ds_bpermute_b32 v231, v184, v35
	s_waitcnt lgkmcnt(0)
	v_bfi_b32 v222, v188, v229, v228
	v_bfi_b32 v223, v188, v231, v230
	ds_bpermute_b32 v228, v185, v36
	ds_bpermute_b32 v229, v185, v32
	ds_bpermute_b32 v230, v185, v37
	ds_bpermute_b32 v231, v185, v33
	s_waitcnt lgkmcnt(0)
	v_bfi_b32 v224, v188, v229, v228
	v_bfi_b32 v225, v188, v231, v230
	ds_bpermute_b32 v228, v185, v38
	ds_bpermute_b32 v229, v185, v34
	ds_bpermute_b32 v230, v185, v39
	ds_bpermute_b32 v231, v185, v35
	s_waitcnt lgkmcnt(0)
	v_bfi_b32 v226, v188, v229, v228
	v_bfi_b32 v227, v188, v231, v230
	global_load_dwordx4 v[36:39], v[174:175], off offset:512
	global_load_dwordx4 v[32:35], v[176:177], off offset:512
	s_waitcnt vmcnt(8)
	v_pk_fma_f32 v[54:55], v[222:223], v[196:197], v[54:55]
	v_pk_fma_f32 v[52:53], v[220:221], v[194:195], v[52:53]
	v_pk_fma_f32 v[46:47], v[226:227], v[196:197], v[46:47]
	v_pk_fma_f32 v[44:45], v[224:225], v[194:195], v[44:45]
	global_store_dwordx4 v[180:181], v[52:55], off offset:512
	global_store_dwordx4 v[198:199], v[44:47], off offset:512
	ds_bpermute_b32 v228, v184, v28
	ds_bpermute_b32 v229, v184, v24
	ds_bpermute_b32 v230, v184, v29
	ds_bpermute_b32 v231, v184, v25
	s_waitcnt lgkmcnt(0)
	v_bfi_b32 v220, v188, v229, v228
	v_bfi_b32 v221, v188, v231, v230
	ds_bpermute_b32 v228, v184, v30
	ds_bpermute_b32 v229, v184, v26
	ds_bpermute_b32 v230, v184, v31
	ds_bpermute_b32 v231, v184, v27
	s_waitcnt lgkmcnt(0)
	v_bfi_b32 v222, v188, v229, v228
	v_bfi_b32 v223, v188, v231, v230
	ds_bpermute_b32 v228, v185, v28
	ds_bpermute_b32 v229, v185, v24
	ds_bpermute_b32 v230, v185, v29
	ds_bpermute_b32 v231, v185, v25
	s_waitcnt lgkmcnt(0)
	v_bfi_b32 v224, v188, v229, v228
	v_bfi_b32 v225, v188, v231, v230
	ds_bpermute_b32 v228, v185, v30
	ds_bpermute_b32 v229, v185, v26
	ds_bpermute_b32 v230, v185, v31
	ds_bpermute_b32 v231, v185, v27
	s_waitcnt lgkmcnt(0)
; #define PG8_BAR __builtin_amdgcn_s_barrier()
; template <class Epi, class Sched, bool ALIGN_EPI = false, bool SP2 = false>
; __device__ __forceinline__ void gemm_phase(PG8_LAS unsigned char* lds, const Gemm g, const Sched& S, const Epi& E) {
;     ...
;         if (!has_next) break;
; #pragma unroll
;         for (int a = 0; a < 2; ++a)
; #pragma unroll
;             for (int b = 0; b < 2; ++b)
; #pragma unroll
;                 for (int m = 0; m < 4; ++m)
; #pragma unroll
;                     for (int n = 0; n < 2; ++n) acc[a][b][m][n] = (f32x4){0.f, 0.f, 0.f, 0.f};
;         cur = nxt; cA = nA; cB = nB; ++ui;
;         if constexpr (ALIGN_EPI) { if (wr == 1) PG8_BAR; }
;     __device__ __forceinline__ void operator()(const pg8::f32x4 (&acc)[2][2][4][2], const pg8::Unit& u, int wr, int wc, int fr, int fq) const {
;     ...
;         for (int ai = 0; ai < 2; ++ai)
; #pragma unroll
;             for (int m = 0; m < 4; ++m) {
;                 float* rowp = base + (size_t)(ai * 128 + wr * 64 + m * 16 + fr) * DM + col0;
; #pragma unroll
;                 for (int bj = 0; bj < 2; ++bj)
; #pragma unroll
;                     for (int n = 0; n < 2; ++n) {
;                         pg8::f32x4* p = (pg8::f32x4*)(rowp + bj * 128 + n * 16);
;                         pg8::f32x4 xv = *p; xv = xv + gv[bj][n] * acc[ai][bj][m][n]; *p = xv;
;                     }
;                 if (m & 1) asm volatile("" ::: "memory");
	v_bfi_b32 v226, v188, v229, v228
	v_bfi_b32 v227, v188, v231, v230
	v_lshl_add_u64 v[178:179], v[168:169], 0, v[162:163]
	ds_bpermute_b32 v180, v184, v178
	ds_bpermute_b32 v181, v184, v179
	ds_bpermute_b32 v198, v185, v178
	ds_bpermute_b32 v199, v185, v179
	s_waitcnt lgkmcnt(0)
	v_lshl_add_u64 v[180:181], v[180:181], 0, v[186:187]
	v_lshl_add_u64 v[198:199], v[198:199], 0, v[186:187]
	global_load_dwordx4 v[28:31], v[180:181], off
	global_load_dwordx4 v[24:27], v[198:199], off
	s_waitcnt vmcnt(8)
	v_pk_fma_f32 v[50:51], v[222:223], v[192:193], v[50:51]
	v_pk_fma_f32 v[48:49], v[220:221], v[190:191], v[48:49]
	v_pk_fma_f32 v[42:43], v[226:227], v[192:193], v[42:43]
	v_pk_fma_f32 v[40:41], v[224:225], v[190:191], v[40:41]
	global_store_dwordx4 v[174:175], v[48:51], off
	global_store_dwordx4 v[176:177], v[40:43], off
	ds_bpermute_b32 v228, v184, v20
	ds_bpermute_b32 v229, v184, v12
	ds_bpermute_b32 v230, v184, v21
	ds_bpermute_b32 v231, v184, v13
	s_waitcnt lgkmcnt(0)
	v_bfi_b32 v220, v188, v229, v228
	v_bfi_b32 v221, v188, v231, v230
	ds_bpermute_b32 v228, v184, v22
	ds_bpermute_b32 v229, v184, v14
	ds_bpermute_b32 v230, v184, v23
	ds_bpermute_b32 v231, v184, v15
	s_waitcnt lgkmcnt(0)
	v_bfi_b32 v222, v188, v229, v228
	v_bfi_b32 v223, v188, v231, v230
	ds_bpermute_b32 v228, v185, v20
	ds_bpermute_b32 v229, v185, v12
	ds_bpermute_b32 v230, v185, v21
	ds_bpermute_b32 v231, v185, v13
	s_waitcnt lgkmcnt(0)
	v_bfi_b32 v224, v188, v229, v228
	v_bfi_b32 v225, v188, v231, v230
	ds_bpermute_b32 v228, v185, v22
	ds_bpermute_b32 v229, v185, v14
	ds_bpermute_b32 v230, v185, v23
	ds_bpermute_b32 v231, v185, v15
	s_waitcnt lgkmcnt(0)
	v_bfi_b32 v226, v188, v229, v228
	v_bfi_b32 v227, v188, v231, v230
	global_load_dwordx4 v[20:23], v[180:181], off offset:512
	global_load_dwordx4 v[12:15], v[198:199], off offset:512
	s_waitcnt vmcnt(8)
	v_pk_fma_f32 v[38:39], v[222:223], v[196:197], v[38:39]
	v_pk_fma_f32 v[36:37], v[220:221], v[194:195], v[36:37]
	v_pk_fma_f32 v[34:35], v[226:227], v[196:197], v[34:35]
	v_pk_fma_f32 v[32:33], v[224:225], v[194:195], v[32:33]
	global_store_dwordx4 v[174:175], v[36:39], off offset:512
	global_store_dwordx4 v[176:177], v[32:35], off offset:512
	ds_bpermute_b32 v228, v184, v16
	ds_bpermute_b32 v229, v184, v8
	ds_bpermute_b32 v230, v184, v17
	ds_bpermute_b32 v231, v184, v9
	s_waitcnt lgkmcnt(0)
	v_bfi_b32 v220, v188, v229, v228
	v_bfi_b32 v221, v188, v231, v230
	ds_bpermute_b32 v228, v184, v18
	ds_bpermute_b32 v229, v184, v10
	ds_bpermute_b32 v230, v184, v19
	ds_bpermute_b32 v231, v184, v11
	s_waitcnt lgkmcnt(0)
	v_bfi_b32 v222, v188, v229, v228
	v_bfi_b32 v223, v188, v231, v230
	ds_bpermute_b32 v228, v185, v16
	ds_bpermute_b32 v229, v185, v8
	ds_bpermute_b32 v230, v185, v17
	ds_bpermute_b32 v231, v185, v9
	s_waitcnt lgkmcnt(0)
	v_bfi_b32 v224, v188, v229, v228
	v_bfi_b32 v225, v188, v231, v230
	ds_bpermute_b32 v228, v185, v18
	ds_bpermute_b32 v229, v185, v10
	ds_bpermute_b32 v230, v185, v19
	ds_bpermute_b32 v231, v185, v11
	s_waitcnt lgkmcnt(0)
	v_bfi_b32 v226, v188, v229, v228
	v_bfi_b32 v227, v188, v231, v230
	s_waitcnt vmcnt(6)
	v_pk_fma_f32 v[30:31], v[222:223], v[192:193], v[30:31]
	v_pk_fma_f32 v[28:29], v[220:221], v[190:191], v[28:29]
	v_pk_fma_f32 v[26:27], v[226:227], v[192:193], v[26:27]
	v_pk_fma_f32 v[24:25], v[224:225], v[190:191], v[24:25]
	global_store_dwordx4 v[180:181], v[28:31], off
	global_store_dwordx4 v[198:199], v[24:27], off
	ds_bpermute_b32 v228, v184, v4
	ds_bpermute_b32 v229, v184, v0
	ds_bpermute_b32 v230, v184, v5
	ds_bpermute_b32 v231, v184, v1
	s_waitcnt lgkmcnt(0)
	v_bfi_b32 v220, v188, v229, v228
	v_bfi_b32 v221, v188, v231, v230
	ds_bpermute_b32 v228, v184, v6
	ds_bpermute_b32 v229, v184, v2
	ds_bpermute_b32 v230, v184, v7
	ds_bpermute_b32 v231, v184, v3
	s_waitcnt lgkmcnt(0)
	v_bfi_b32 v222, v188, v229, v228
	v_bfi_b32 v223, v188, v231, v230
	ds_bpermute_b32 v228, v185, v4
	ds_bpermute_b32 v229, v185, v0
	ds_bpermute_b32 v230, v185, v5
	ds_bpermute_b32 v231, v185, v1
	s_waitcnt lgkmcnt(0)
	v_bfi_b32 v224, v188, v229, v228
	v_bfi_b32 v225, v188, v231, v230
	ds_bpermute_b32 v228, v185, v6
	ds_bpermute_b32 v229, v185, v2
	ds_bpermute_b32 v230, v185, v7
	ds_bpermute_b32 v231, v185, v3
	s_waitcnt lgkmcnt(0)
	v_bfi_b32 v226, v188, v229, v228
	v_bfi_b32 v227, v188, v231, v230
	s_waitcnt vmcnt(4)
	v_pk_fma_f32 v[22:23], v[222:223], v[196:197], v[22:23]
	v_pk_fma_f32 v[20:21], v[220:221], v[194:195], v[20:21]
	v_pk_fma_f32 v[14:15], v[226:227], v[196:197], v[14:15]
	v_pk_fma_f32 v[12:13], v[224:225], v[194:195], v[12:13]
	global_store_dwordx4 v[180:181], v[20:23], off offset:512
	global_store_dwordx4 v[198:199], v[12:15], off offset:512
	s_cbranch_vccnz .LBB0_1085
	s_andn2_b64 vcc, exec, s[0:1]
	s_cbranch_vccnz .LBB0_1084
	s_barrier
	s_branch .LBB0_1084

;     __device__ __forceinline__ void operator()(const pg8::f32x4 (&acc)[2][2][4][2], const pg8::Unit& u, int wr, int wc, int fr, int fq) const {
;         const int b = u.pm / 9, j = u.pm - b * 9;
;         float* base = (j == 0) ? xc + (size_t)b * CTX * DM : out + ((size_t)b * SEQ + (size_t)(j - 1) * 256) * DM;
;         const float* g = gate + (size_t)((j == 0) ? 16 : b) * MODW;
;         const int col0 = u.pn * 256 + wc * 32 + 4 * fq;
;         pg8::f32x4 gv[2][2];
; #pragma unroll
;         for (int bj = 0; bj < 2; ++bj)
; #pragma unroll
;             for (int n = 0; n < 2; ++n) gv[bj][n] = *(const pg8::f32x4*)(g + col0 + bj * 128 + n * 16);
; #pragma unroll
;         for (int ai = 0; ai < 2; ++ai)
; #pragma unroll
;             for (int m = 0; m < 4; ++m) {
;                 float* rowp = base + (size_t)(ai * 128 + wr * 64 + m * 16 + fr) * DM + col0;
; #pragma unroll
;                 for (int bj = 0; bj < 2; ++bj)
; #pragma unroll
;                     for (int n = 0; n < 2; ++n) {
;                         pg8::f32x4* p = (pg8::f32x4*)(rowp + bj * 128 + n * 16);
;                         pg8::f32x4 xv = *p; xv = xv + gv[bj][n] * acc[ai][bj][m][n]; *p = xv;
;                     }
.LBB0_1129:
	s_lshl_b64 s[12:13], s[56:57], 2
	v_lshl_or_b32 v88, s15, 8, v171
	s_add_u32 s12, s11, s12
	v_ashrrev_i32_e32 v89, 31, v88
	s_addc_u32 s13, s24, s13
	v_lshlrev_b64 v[168:169], 2, v[88:89]
	v_lshl_add_u64 v[88:89], s[12:13], 0, v[168:169]
	v_lshl_add_u64 v[168:169], s[48:49], 0, v[168:169]
	v_lshl_add_u64 v[178:179], v[168:169], 0, v[148:149]
	global_load_dwordx4 v[108:111], v[88:89], off
	global_load_dwordx4 v[104:107], v[88:89], off offset:64
	global_load_dwordx4 v[100:103], v[88:89], off offset:512
	s_nop 0
	global_load_dwordx4 v[88:91], v[88:89], off offset:576
	s_mov_b64 s[48:49], -1
	s_and_b64 vcc, exec, s[38:39]
	s_waitcnt vmcnt(0)
	v_and_b32_e32 v228, 63, v200
	v_lshrrev_b32_e32 v229, 3, v228
	v_and_b32_e32 v184, 3, v228
	v_lshl_or_b32 v184, v184, 4, v229
	v_lshlrev_b32_e32 v184, 2, v184
	v_add_u32_e32 v185, 32, v184
	v_bfe_u32 v229, v228, 2, 1
	v_lshlrev_b32_e32 v186, 6, v229
	v_mov_b32_e32 v187, 0
	v_sub_u32_e32 v188, 0, v229
	ds_bpermute_b32 v228, v184, v108
	ds_bpermute_b32 v229, v184, v104
	s_waitcnt lgkmcnt(0)
	v_bfi_b32 v190, v188, v229, v228
	ds_bpermute_b32 v228, v184, v109
	ds_bpermute_b32 v229, v184, v105
	s_waitcnt lgkmcnt(0)
	v_bfi_b32 v191, v188, v229, v228
	ds_bpermute_b32 v228, v184, v110
	ds_bpermute_b32 v229, v184, v106
	s_waitcnt lgkmcnt(0)
	v_bfi_b32 v192, v188, v229, v228
	ds_bpermute_b32 v228, v184, v111
	ds_bpermute_b32 v229, v184, v107
	s_waitcnt lgkmcnt(0)
	v_bfi_b32 v193, v188, v229, v228
	ds_bpermute_b32 v228, v184, v100
	ds_bpermute_b32 v229, v184, v88
	s_waitcnt lgkmcnt(0)
	v_bfi_b32 v194, v188, v229, v228
	ds_bpermute_b32 v228, v184, v101
	ds_bpermute_b32 v229, v184, v89
	s_waitcnt lgkmcnt(0)
	v_bfi_b32 v195, v188, v229, v228
	ds_bpermute_b32 v228, v184, v102
	ds_bpermute_b32 v229, v184, v90
	s_waitcnt lgkmcnt(0)
	v_bfi_b32 v196, v188, v229, v228
	ds_bpermute_b32 v228, v184, v103
	ds_bpermute_b32 v229, v184, v91
	s_waitcnt lgkmcnt(0)
	v_bfi_b32 v197, v188, v229, v228
	v_lshl_add_u64 v[178:179], v[168:169], 0, v[148:149]
	ds_bpermute_b32 v174, v184, v178
	ds_bpermute_b32 v175, v184, v179
	ds_bpermute_b32 v176, v185, v178
	ds_bpermute_b32 v177, v185, v179
	s_waitcnt lgkmcnt(0)
	v_lshl_add_u64 v[174:175], v[174:175], 0, v[186:187]
	v_lshl_add_u64 v[176:177], v[176:177], 0, v[186:187]
	global_load_dwordx4 v[204:207], v[174:175], off
	global_load_dwordx4 v[208:211], v[176:177], off
	global_load_dwordx4 v[212:215], v[174:175], off offset:512
	global_load_dwordx4 v[216:219], v[176:177], off offset:512
	ds_bpermute_b32 v228, v184, v142
	ds_bpermute_b32 v229, v184, v138
	ds_bpermute_b32 v230, v184, v143
	ds_bpermute_b32 v231, v184, v139
	s_waitcnt lgkmcnt(0)
	v_bfi_b32 v220, v188, v229, v228
	v_bfi_b32 v221, v188, v231, v230
	ds_bpermute_b32 v228, v184, v144
	ds_bpermute_b32 v229, v184, v140
	ds_bpermute_b32 v230, v184, v145
	ds_bpermute_b32 v231, v184, v141
	s_waitcnt lgkmcnt(0)
	v_bfi_b32 v222, v188, v229, v228
	v_bfi_b32 v223, v188, v231, v230
	ds_bpermute_b32 v228, v185, v142
	ds_bpermute_b32 v229, v185, v138
	ds_bpermute_b32 v230, v185, v143
	ds_bpermute_b32 v231, v185, v139
	s_waitcnt lgkmcnt(0)
	v_bfi_b32 v224, v188, v229, v228
	v_bfi_b32 v225, v188, v231, v230
	ds_bpermute_b32 v228, v185, v144
	ds_bpermute_b32 v229, v185, v140
	ds_bpermute_b32 v230, v185, v145
	ds_bpermute_b32 v231, v185, v141
	s_waitcnt lgkmcnt(0)
	v_bfi_b32 v226, v188, v229, v228
	v_bfi_b32 v227, v188, v231, v230
	v_lshl_add_u64 v[178:179], v[168:169], 0, v[150:151]
	ds_bpermute_b32 v180, v184, v178
	ds_bpermute_b32 v181, v184, v179
	ds_bpermute_b32 v198, v185, v178
	ds_bpermute_b32 v199, v185, v179
	s_waitcnt lgkmcnt(0)
	v_lshl_add_u64 v[180:181], v[180:181], 0, v[186:187]
	v_lshl_add_u64 v[198:199], v[198:199], 0, v[186:187]
	global_load_dwordx4 v[142:145], v[180:181], off
	global_load_dwordx4 v[138:141], v[198:199], off
	s_waitcnt vmcnt(4)
	v_pk_fma_f32 v[206:207], v[222:223], v[192:193], v[206:207]
	v_pk_fma_f32 v[204:205], v[220:221], v[190:191], v[204:205]
	v_pk_fma_f32 v[210:211], v[226:227], v[192:193], v[210:211]
	v_pk_fma_f32 v[208:209], v[224:225], v[190:191], v[208:209]
	global_store_dwordx4 v[174:175], v[204:207], off
	global_store_dwordx4 v[176:177], v[208:211], off
	ds_bpermute_b32 v228, v184, v134
	ds_bpermute_b32 v229, v184, v124
	ds_bpermute_b32 v230, v184, v135
	ds_bpermute_b32 v231, v184, v125
	s_waitcnt lgkmcnt(0)
	v_bfi_b32 v220, v188, v229, v228
	v_bfi_b32 v221, v188, v231, v230
	ds_bpermute_b32 v228, v184, v136
	ds_bpermute_b32 v229, v184, v126
	ds_bpermute_b32 v230, v184, v137
	ds_bpermute_b32 v231, v184, v127
	s_waitcnt lgkmcnt(0)
	v_bfi_b32 v222, v188, v229, v228
	v_bfi_b32 v223, v188, v231, v230
	ds_bpermute_b32 v228, v185, v134
	ds_bpermute_b32 v229, v185, v124
	ds_bpermute_b32 v230, v185, v135
	ds_bpermute_b32 v231, v185, v125
	s_waitcnt lgkmcnt(0)
	v_bfi_b32 v224, v188, v229, v228
	v_bfi_b32 v225, v188, v231, v230
	ds_bpermute_b32 v228, v185, v136
	ds_bpermute_b32 v229, v185, v126
	ds_bpermute_b32 v230, v185, v137
	ds_bpermute_b32 v231, v185, v127
	s_waitcnt lgkmcnt(0)
	v_bfi_b32 v226, v188, v229, v228
	v_bfi_b32 v227, v188, v231, v230
	global_load_dwordx4 v[134:137], v[180:181], off offset:512
	global_load_dwordx4 v[124:127], v[198:199], off offset:512
	s_waitcnt vmcnt(6)
	v_pk_fma_f32 v[214:215], v[222:223], v[196:197], v[214:215]
	v_pk_fma_f32 v[212:213], v[220:221], v[194:195], v[212:213]
	v_pk_fma_f32 v[218:219], v[226:227], v[196:197], v[218:219]
	v_pk_fma_f32 v[216:217], v[224:225], v[194:195], v[216:217]
	global_store_dwordx4 v[174:175], v[212:215], off offset:512
	global_store_dwordx4 v[176:177], v[216:219], off offset:512
	ds_bpermute_b32 v228, v184, v130
	ds_bpermute_b32 v229, v184, v120
	ds_bpermute_b32 v230, v184, v131
	ds_bpermute_b32 v231, v184, v121
	s_waitcnt lgkmcnt(0)
;     __device__ __forceinline__ void operator()(const pg8::f32x4 (&acc)[2][2][4][2], const pg8::Unit& u, int wr, int wc, int fr, int fq) const {
;     ...
;         for (int ai = 0; ai < 2; ++ai)
; #pragma unroll
;             for (int m = 0; m < 4; ++m) {
;                 float* rowp = base + (size_t)(ai * 128 + wr * 64 + m * 16 + fr) * DM + col0;
; #pragma unroll
;                 for (int bj = 0; bj < 2; ++bj)
; #pragma unroll
;                     for (int n = 0; n < 2; ++n) {
;                         pg8::f32x4* p = (pg8::f32x4*)(rowp + bj * 128 + n * 16);
;                         pg8::f32x4 xv = *p; xv = xv + gv[bj][n] * acc[ai][bj][m][n]; *p = xv;
;                     }
	v_bfi_b32 v220, v188, v229, v228
	v_bfi_b32 v221, v188, v231, v230
	ds_bpermute_b32 v228, v184, v132
	ds_bpermute_b32 v229, v184, v122
	ds_bpermute_b32 v230, v184, v133
	ds_bpermute_b32 v231, v184, v123
	s_waitcnt lgkmcnt(0)
	v_bfi_b32 v222, v188, v229, v228
	v_bfi_b32 v223, v188, v231, v230
	ds_bpermute_b32 v228, v185, v130
	ds_bpermute_b32 v229, v185, v120
	ds_bpermute_b32 v230, v185, v131
	ds_bpermute_b32 v231, v185, v121
	s_waitcnt lgkmcnt(0)
	v_bfi_b32 v224, v188, v229, v228
	v_bfi_b32 v225, v188, v231, v230
	ds_bpermute_b32 v228, v185, v132
	ds_bpermute_b32 v229, v185, v122
	ds_bpermute_b32 v230, v185, v133
	ds_bpermute_b32 v231, v185, v123
	s_waitcnt lgkmcnt(0)
	v_bfi_b32 v226, v188, v229, v228
	v_bfi_b32 v227, v188, v231, v230
	v_lshl_add_u64 v[178:179], v[168:169], 0, v[152:153]
	ds_bpermute_b32 v174, v184, v178
	ds_bpermute_b32 v175, v184, v179
	ds_bpermute_b32 v176, v185, v178
	ds_bpermute_b32 v177, v185, v179
	s_waitcnt lgkmcnt(0)
	v_lshl_add_u64 v[174:175], v[174:175], 0, v[186:187]
	v_lshl_add_u64 v[176:177], v[176:177], 0, v[186:187]
	global_load_dwordx4 v[130:133], v[174:175], off
	global_load_dwordx4 v[120:123], v[176:177], off
	s_waitcnt vmcnt(8)
	v_pk_fma_f32 v[144:145], v[222:223], v[192:193], v[144:145]
	v_pk_fma_f32 v[142:143], v[220:221], v[190:191], v[142:143]
	v_pk_fma_f32 v[140:141], v[226:227], v[192:193], v[140:141]
	v_pk_fma_f32 v[138:139], v[224:225], v[190:191], v[138:139]
	global_store_dwordx4 v[180:181], v[142:145], off
	global_store_dwordx4 v[198:199], v[138:141], off
	ds_bpermute_b32 v228, v184, v116
	ds_bpermute_b32 v229, v184, v112
	ds_bpermute_b32 v230, v184, v117
	ds_bpermute_b32 v231, v184, v113
	s_waitcnt lgkmcnt(0)
	v_bfi_b32 v220, v188, v229, v228
	v_bfi_b32 v221, v188, v231, v230
	ds_bpermute_b32 v228, v184, v118
	ds_bpermute_b32 v229, v184, v114
	ds_bpermute_b32 v230, v184, v119
	ds_bpermute_b32 v231, v184, v115
	s_waitcnt lgkmcnt(0)
	v_bfi_b32 v222, v188, v229, v228
	v_bfi_b32 v223, v188, v231, v230
	ds_bpermute_b32 v228, v185, v116
	ds_bpermute_b32 v229, v185, v112
	ds_bpermute_b32 v230, v185, v117
	ds_bpermute_b32 v231, v185, v113
	s_waitcnt lgkmcnt(0)
	v_bfi_b32 v224, v188, v229, v228
	v_bfi_b32 v225, v188, v231, v230
	ds_bpermute_b32 v228, v185, v118
	ds_bpermute_b32 v229, v185, v114
	ds_bpermute_b32 v230, v185, v119
	ds_bpermute_b32 v231, v185, v115
	s_waitcnt lgkmcnt(0)
	v_bfi_b32 v226, v188, v229, v228
	v_bfi_b32 v227, v188, v231, v230
	global_load_dwordx4 v[116:119], v[174:175], off offset:512
	global_load_dwordx4 v[112:115], v[176:177], off offset:512
	s_waitcnt vmcnt(8)
	v_pk_fma_f32 v[136:137], v[222:223], v[196:197], v[136:137]
	v_pk_fma_f32 v[134:135], v[220:221], v[194:195], v[134:135]
	v_pk_fma_f32 v[126:127], v[226:227], v[196:197], v[126:127]
	v_pk_fma_f32 v[124:125], v[224:225], v[194:195], v[124:125]
	global_store_dwordx4 v[180:181], v[134:137], off offset:512
	global_store_dwordx4 v[198:199], v[124:127], off offset:512
	ds_bpermute_b32 v228, v184, v96
	ds_bpermute_b32 v229, v184, v92
	ds_bpermute_b32 v230, v184, v97
	ds_bpermute_b32 v231, v184, v93
	s_waitcnt lgkmcnt(0)
	v_bfi_b32 v220, v188, v229, v228
	v_bfi_b32 v221, v188, v231, v230
	ds_bpermute_b32 v228, v184, v98
	ds_bpermute_b32 v229, v184, v94
	ds_bpermute_b32 v230, v184, v99
	ds_bpermute_b32 v231, v184, v95
	s_waitcnt lgkmcnt(0)
	v_bfi_b32 v222, v188, v229, v228
	v_bfi_b32 v223, v188, v231, v230
	ds_bpermute_b32 v228, v185, v96
	ds_bpermute_b32 v229, v185, v92
	ds_bpermute_b32 v230, v185, v97
	ds_bpermute_b32 v231, v185, v93
	s_waitcnt lgkmcnt(0)
	v_bfi_b32 v224, v188, v229, v228
	v_bfi_b32 v225, v188, v231, v230
	ds_bpermute_b32 v228, v185, v98
	ds_bpermute_b32 v229, v185, v94
	ds_bpermute_b32 v230, v185, v99
	ds_bpermute_b32 v231, v185, v95
	s_waitcnt lgkmcnt(0)
	v_bfi_b32 v226, v188, v229, v228
	v_bfi_b32 v227, v188, v231, v230
	v_lshl_add_u64 v[178:179], v[168:169], 0, v[154:155]
	ds_bpermute_b32 v180, v184, v178
	ds_bpermute_b32 v181, v184, v179
	ds_bpermute_b32 v198, v185, v178
	ds_bpermute_b32 v199, v185, v179
	s_waitcnt lgkmcnt(0)
	v_lshl_add_u64 v[180:181], v[180:181], 0, v[186:187]
	v_lshl_add_u64 v[198:199], v[198:199], 0, v[186:187]
	global_load_dwordx4 v[96:99], v[180:181], off
	global_load_dwordx4 v[92:95], v[198:199], off
	s_waitcnt vmcnt(8)
	v_pk_fma_f32 v[132:133], v[222:223], v[192:193], v[132:133]
	v_pk_fma_f32 v[130:131], v[220:221], v[190:191], v[130:131]
	v_pk_fma_f32 v[122:123], v[226:227], v[192:193], v[122:123]
	v_pk_fma_f32 v[120:121], v[224:225], v[190:191], v[120:121]
	global_store_dwordx4 v[174:175], v[130:133], off
	global_store_dwordx4 v[176:177], v[120:123], off
	ds_bpermute_b32 v228, v184, v84
	ds_bpermute_b32 v229, v184, v76
	ds_bpermute_b32 v230, v184, v85
	ds_bpermute_b32 v231, v184, v77
	s_waitcnt lgkmcnt(0)
	v_bfi_b32 v220, v188, v229, v228
	v_bfi_b32 v221, v188, v231, v230
	ds_bpermute_b32 v228, v184, v86
	ds_bpermute_b32 v229, v184, v78
	ds_bpermute_b32 v230, v184, v87
	ds_bpermute_b32 v231, v184, v79
	s_waitcnt lgkmcnt(0)
	v_bfi_b32 v222, v188, v229, v228
	v_bfi_b32 v223, v188, v231, v230
	ds_bpermute_b32 v228, v185, v84
	ds_bpermute_b32 v229, v185, v76
	ds_bpermute_b32 v230, v185, v85
	ds_bpermute_b32 v231, v185, v77
	s_waitcnt lgkmcnt(0)
	v_bfi_b32 v224, v188, v229, v228
	v_bfi_b32 v225, v188, v231, v230
	ds_bpermute_b32 v228, v185, v86
	ds_bpermute_b32 v229, v185, v78
	ds_bpermute_b32 v230, v185, v87
	ds_bpermute_b32 v231, v185, v79
	s_waitcnt lgkmcnt(0)
	v_bfi_b32 v226, v188, v229, v228
	v_bfi_b32 v227, v188, v231, v230
	global_load_dwordx4 v[84:87], v[180:181], off offset:512
	global_load_dwordx4 v[76:79], v[198:199], off offset:512
	s_waitcnt vmcnt(8)
;     __device__ __forceinline__ void operator()(const pg8::f32x4 (&acc)[2][2][4][2], const pg8::Unit& u, int wr, int wc, int fr, int fq) const {
;     ...
;         for (int ai = 0; ai < 2; ++ai)
; #pragma unroll
;             for (int m = 0; m < 4; ++m) {
;                 float* rowp = base + (size_t)(ai * 128 + wr * 64 + m * 16 + fr) * DM + col0;
; #pragma unroll
;                 for (int bj = 0; bj < 2; ++bj)
; #pragma unroll
;                     for (int n = 0; n < 2; ++n) {
;                         pg8::f32x4* p = (pg8::f32x4*)(rowp + bj * 128 + n * 16);
;                         pg8::f32x4 xv = *p; xv = xv + gv[bj][n] * acc[ai][bj][m][n]; *p = xv;
;                     }
	v_pk_fma_f32 v[118:119], v[222:223], v[196:197], v[118:119]
	v_pk_fma_f32 v[116:117], v[220:221], v[194:195], v[116:117]
	v_pk_fma_f32 v[114:115], v[226:227], v[196:197], v[114:115]
	v_pk_fma_f32 v[112:113], v[224:225], v[194:195], v[112:113]
	global_store_dwordx4 v[174:175], v[116:119], off offset:512
	global_store_dwordx4 v[176:177], v[112:115], off offset:512
	ds_bpermute_b32 v228, v184, v80
	ds_bpermute_b32 v229, v184, v72
	ds_bpermute_b32 v230, v184, v81
	ds_bpermute_b32 v231, v184, v73
	s_waitcnt lgkmcnt(0)
	v_bfi_b32 v220, v188, v229, v228
	v_bfi_b32 v221, v188, v231, v230
	ds_bpermute_b32 v228, v184, v82
	ds_bpermute_b32 v229, v184, v74
	ds_bpermute_b32 v230, v184, v83
	ds_bpermute_b32 v231, v184, v75
	s_waitcnt lgkmcnt(0)
	v_bfi_b32 v222, v188, v229, v228
	v_bfi_b32 v223, v188, v231, v230
	ds_bpermute_b32 v228, v185, v80
	ds_bpermute_b32 v229, v185, v72
	ds_bpermute_b32 v230, v185, v81
	ds_bpermute_b32 v231, v185, v73
	s_waitcnt lgkmcnt(0)
	v_bfi_b32 v224, v188, v229, v228
	v_bfi_b32 v225, v188, v231, v230
	ds_bpermute_b32 v228, v185, v82
	ds_bpermute_b32 v229, v185, v74
	ds_bpermute_b32 v230, v185, v83
	ds_bpermute_b32 v231, v185, v75
	s_waitcnt lgkmcnt(0)
	v_bfi_b32 v226, v188, v229, v228
	v_bfi_b32 v227, v188, v231, v230
	v_lshl_add_u64 v[178:179], v[168:169], 0, v[156:157]
	ds_bpermute_b32 v174, v184, v178
	ds_bpermute_b32 v175, v184, v179
	ds_bpermute_b32 v176, v185, v178
	ds_bpermute_b32 v177, v185, v179
	s_waitcnt lgkmcnt(0)
	v_lshl_add_u64 v[174:175], v[174:175], 0, v[186:187]
	v_lshl_add_u64 v[176:177], v[176:177], 0, v[186:187]
	global_load_dwordx4 v[80:83], v[174:175], off
	global_load_dwordx4 v[72:75], v[176:177], off
	s_waitcnt vmcnt(8)
	v_pk_fma_f32 v[98:99], v[222:223], v[192:193], v[98:99]
	v_pk_fma_f32 v[96:97], v[220:221], v[190:191], v[96:97]
	v_pk_fma_f32 v[94:95], v[226:227], v[192:193], v[94:95]
	v_pk_fma_f32 v[92:93], v[224:225], v[190:191], v[92:93]
	global_store_dwordx4 v[180:181], v[96:99], off
	global_store_dwordx4 v[198:199], v[92:95], off
	ds_bpermute_b32 v228, v184, v68
	ds_bpermute_b32 v229, v184, v64
	ds_bpermute_b32 v230, v184, v69
	ds_bpermute_b32 v231, v184, v65
	s_waitcnt lgkmcnt(0)
	v_bfi_b32 v220, v188, v229, v228
	v_bfi_b32 v221, v188, v231, v230
	ds_bpermute_b32 v228, v184, v70
	ds_bpermute_b32 v229, v184, v66
	ds_bpermute_b32 v230, v184, v71
	ds_bpermute_b32 v231, v184, v67
	s_waitcnt lgkmcnt(0)
	v_bfi_b32 v222, v188, v229, v228
	v_bfi_b32 v223, v188, v231, v230
	ds_bpermute_b32 v228, v185, v68
	ds_bpermute_b32 v229, v185, v64
	ds_bpermute_b32 v230, v185, v69
	ds_bpermute_b32 v231, v185, v65
	s_waitcnt lgkmcnt(0)
	v_bfi_b32 v224, v188, v229, v228
	v_bfi_b32 v225, v188, v231, v230
	ds_bpermute_b32 v228, v185, v70
	ds_bpermute_b32 v229, v185, v66
	ds_bpermute_b32 v230, v185, v71
	ds_bpermute_b32 v231, v185, v67
	s_waitcnt lgkmcnt(0)
	v_bfi_b32 v226, v188, v229, v228
	v_bfi_b32 v227, v188, v231, v230
	global_load_dwordx4 v[68:71], v[174:175], off offset:512
	global_load_dwordx4 v[64:67], v[176:177], off offset:512
	s_waitcnt vmcnt(8)
	v_pk_fma_f32 v[86:87], v[222:223], v[196:197], v[86:87]
	v_pk_fma_f32 v[84:85], v[220:221], v[194:195], v[84:85]
	v_pk_fma_f32 v[78:79], v[226:227], v[196:197], v[78:79]
	v_pk_fma_f32 v[76:77], v[224:225], v[194:195], v[76:77]
	global_store_dwordx4 v[180:181], v[84:87], off offset:512
	global_store_dwordx4 v[198:199], v[76:79], off offset:512
	ds_bpermute_b32 v228, v184, v60
	ds_bpermute_b32 v229, v184, v56
	ds_bpermute_b32 v230, v184, v61
	ds_bpermute_b32 v231, v184, v57
	s_waitcnt lgkmcnt(0)
	v_bfi_b32 v220, v188, v229, v228
	v_bfi_b32 v221, v188, v231, v230
	ds_bpermute_b32 v228, v184, v62
	ds_bpermute_b32 v229, v184, v58
	ds_bpermute_b32 v230, v184, v63
	ds_bpermute_b32 v231, v184, v59
	s_waitcnt lgkmcnt(0)
	v_bfi_b32 v222, v188, v229, v228
	v_bfi_b32 v223, v188, v231, v230
	ds_bpermute_b32 v228, v185, v60
	ds_bpermute_b32 v229, v185, v56
	ds_bpermute_b32 v230, v185, v61
	ds_bpermute_b32 v231, v185, v57
	s_waitcnt lgkmcnt(0)
	v_bfi_b32 v224, v188, v229, v228
	v_bfi_b32 v225, v188, v231, v230
	ds_bpermute_b32 v228, v185, v62
	ds_bpermute_b32 v229, v185, v58
	ds_bpermute_b32 v230, v185, v63
	ds_bpermute_b32 v231, v185, v59
	s_waitcnt lgkmcnt(0)
	v_bfi_b32 v226, v188, v229, v228
	v_bfi_b32 v227, v188, v231, v230
	v_lshl_add_u64 v[178:179], v[168:169], 0, v[158:159]
	ds_bpermute_b32 v180, v184, v178
	ds_bpermute_b32 v181, v184, v179
	ds_bpermute_b32 v198, v185, v178
	ds_bpermute_b32 v199, v185, v179
	s_waitcnt lgkmcnt(0)
	v_lshl_add_u64 v[180:181], v[180:181], 0, v[186:187]
	v_lshl_add_u64 v[198:199], v[198:199], 0, v[186:187]
	global_load_dwordx4 v[60:63], v[180:181], off
	global_load_dwordx4 v[56:59], v[198:199], off
	s_waitcnt vmcnt(8)
	v_pk_fma_f32 v[82:83], v[222:223], v[192:193], v[82:83]
	v_pk_fma_f32 v[80:81], v[220:221], v[190:191], v[80:81]
	v_pk_fma_f32 v[74:75], v[226:227], v[192:193], v[74:75]
	v_pk_fma_f32 v[72:73], v[224:225], v[190:191], v[72:73]
	global_store_dwordx4 v[174:175], v[80:83], off
	global_store_dwordx4 v[176:177], v[72:75], off
	ds_bpermute_b32 v228, v184, v52
	ds_bpermute_b32 v229, v184, v44
	ds_bpermute_b32 v230, v184, v53
	ds_bpermute_b32 v231, v184, v45
	s_waitcnt lgkmcnt(0)
	v_bfi_b32 v220, v188, v229, v228
	v_bfi_b32 v221, v188, v231, v230
	ds_bpermute_b32 v228, v184, v54
	ds_bpermute_b32 v229, v184, v46
	ds_bpermute_b32 v230, v184, v55
	ds_bpermute_b32 v231, v184, v47
	s_waitcnt lgkmcnt(0)
	v_bfi_b32 v222, v188, v229, v228
	v_bfi_b32 v223, v188, v231, v230
	ds_bpermute_b32 v228, v185, v52
	ds_bpermute_b32 v229, v185, v44
	ds_bpermute_b32 v230, v185, v53
	ds_bpermute_b32 v231, v185, v45
	s_waitcnt lgkmcnt(0)
;     __device__ __forceinline__ void operator()(const pg8::f32x4 (&acc)[2][2][4][2], const pg8::Unit& u, int wr, int wc, int fr, int fq) const {
;     ...
;         for (int ai = 0; ai < 2; ++ai)
; #pragma unroll
;             for (int m = 0; m < 4; ++m) {
;                 float* rowp = base + (size_t)(ai * 128 + wr * 64 + m * 16 + fr) * DM + col0;
; #pragma unroll
;                 for (int bj = 0; bj < 2; ++bj)
; #pragma unroll
;                     for (int n = 0; n < 2; ++n) {
;                         pg8::f32x4* p = (pg8::f32x4*)(rowp + bj * 128 + n * 16);
;                         pg8::f32x4 xv = *p; xv = xv + gv[bj][n] * acc[ai][bj][m][n]; *p = xv;
;                     }
	v_bfi_b32 v224, v188, v229, v228
	v_bfi_b32 v225, v188, v231, v230
	ds_bpermute_b32 v228, v185, v54
	ds_bpermute_b32 v229, v185, v46
	ds_bpermute_b32 v230, v185, v55
	ds_bpermute_b32 v231, v185, v47
	s_waitcnt lgkmcnt(0)
	v_bfi_b32 v226, v188, v229, v228
	v_bfi_b32 v227, v188, v231, v230
	global_load_dwordx4 v[52:55], v[180:181], off offset:512
	global_load_dwordx4 v[44:47], v[198:199], off offset:512
	s_waitcnt vmcnt(8)
	v_pk_fma_f32 v[70:71], v[222:223], v[196:197], v[70:71]
	v_pk_fma_f32 v[68:69], v[220:221], v[194:195], v[68:69]
	v_pk_fma_f32 v[66:67], v[226:227], v[196:197], v[66:67]
	v_pk_fma_f32 v[64:65], v[224:225], v[194:195], v[64:65]
	global_store_dwordx4 v[174:175], v[68:71], off offset:512
	global_store_dwordx4 v[176:177], v[64:67], off offset:512
	ds_bpermute_b32 v228, v184, v48
	ds_bpermute_b32 v229, v184, v40
	ds_bpermute_b32 v230, v184, v49
	ds_bpermute_b32 v231, v184, v41
	s_waitcnt lgkmcnt(0)
	v_bfi_b32 v220, v188, v229, v228
	v_bfi_b32 v221, v188, v231, v230
	ds_bpermute_b32 v228, v184, v50
	ds_bpermute_b32 v229, v184, v42
	ds_bpermute_b32 v230, v184, v51
	ds_bpermute_b32 v231, v184, v43
	s_waitcnt lgkmcnt(0)
	v_bfi_b32 v222, v188, v229, v228
	v_bfi_b32 v223, v188, v231, v230
	ds_bpermute_b32 v228, v185, v48
	ds_bpermute_b32 v229, v185, v40
	ds_bpermute_b32 v230, v185, v49
	ds_bpermute_b32 v231, v185, v41
	s_waitcnt lgkmcnt(0)
	v_bfi_b32 v224, v188, v229, v228
	v_bfi_b32 v225, v188, v231, v230
	ds_bpermute_b32 v228, v185, v50
	ds_bpermute_b32 v229, v185, v42
	ds_bpermute_b32 v230, v185, v51
	ds_bpermute_b32 v231, v185, v43
	s_waitcnt lgkmcnt(0)
	v_bfi_b32 v226, v188, v229, v228
	v_bfi_b32 v227, v188, v231, v230
	v_lshl_add_u64 v[178:179], v[168:169], 0, v[160:161]
	ds_bpermute_b32 v174, v184, v178
	ds_bpermute_b32 v175, v184, v179
	ds_bpermute_b32 v176, v185, v178
	ds_bpermute_b32 v177, v185, v179
	s_waitcnt lgkmcnt(0)
	v_lshl_add_u64 v[174:175], v[174:175], 0, v[186:187]
	v_lshl_add_u64 v[176:177], v[176:177], 0, v[186:187]
	global_load_dwordx4 v[48:51], v[174:175], off
	global_load_dwordx4 v[40:43], v[176:177], off
	s_waitcnt vmcnt(8)
	v_pk_fma_f32 v[62:63], v[222:223], v[192:193], v[62:63]
	v_pk_fma_f32 v[60:61], v[220:221], v[190:191], v[60:61]
	v_pk_fma_f32 v[58:59], v[226:227], v[192:193], v[58:59]
	v_pk_fma_f32 v[56:57], v[224:225], v[190:191], v[56:57]
	global_store_dwordx4 v[180:181], v[60:63], off
	global_store_dwordx4 v[198:199], v[56:59], off
	ds_bpermute_b32 v228, v184, v36
	ds_bpermute_b32 v229, v184, v32
	ds_bpermute_b32 v230, v184, v37
	ds_bpermute_b32 v231, v184, v33
	s_waitcnt lgkmcnt(0)
	v_bfi_b32 v220, v188, v229, v228
	v_bfi_b32 v221, v188, v231, v230
	ds_bpermute_b32 v228, v184, v38
	ds_bpermute_b32 v229, v184, v34
	ds_bpermute_b32 v230, v184, v39
	ds_bpermute_b32 v231, v184, v35
	s_waitcnt lgkmcnt(0)
	v_bfi_b32 v222, v188, v229, v228
	v_bfi_b32 v223, v188, v231, v230
	ds_bpermute_b32 v228, v185, v36
	ds_bpermute_b32 v229, v185, v32
	ds_bpermute_b32 v230, v185, v37
	ds_bpermute_b32 v231, v185, v33
	s_waitcnt lgkmcnt(0)
	v_bfi_b32 v224, v188, v229, v228
	v_bfi_b32 v225, v188, v231, v230
	ds_bpermute_b32 v228, v185, v38
	ds_bpermute_b32 v229, v185, v34
	ds_bpermute_b32 v230, v185, v39
	ds_bpermute_b32 v231, v185, v35
	s_waitcnt lgkmcnt(0)
	v_bfi_b32 v226, v188, v229, v228
	v_bfi_b32 v227, v188, v231, v230
	global_load_dwordx4 v[36:39], v[174:175], off offset:512
	global_load_dwordx4 v[32:35], v[176:177], off offset:512
	s_waitcnt vmcnt(8)
	v_pk_fma_f32 v[54:55], v[222:223], v[196:197], v[54:55]
	v_pk_fma_f32 v[52:53], v[220:221], v[194:195], v[52:53]
	v_pk_fma_f32 v[46:47], v[226:227], v[196:197], v[46:47]
	v_pk_fma_f32 v[44:45], v[224:225], v[194:195], v[44:45]
	global_store_dwordx4 v[180:181], v[52:55], off offset:512
	global_store_dwordx4 v[198:199], v[44:47], off offset:512
	ds_bpermute_b32 v228, v184, v28
	ds_bpermute_b32 v229, v184, v24
	ds_bpermute_b32 v230, v184, v29
	ds_bpermute_b32 v231, v184, v25
	s_waitcnt lgkmcnt(0)
	v_bfi_b32 v220, v188, v229, v228
	v_bfi_b32 v221, v188, v231, v230
	ds_bpermute_b32 v228, v184, v30
	ds_bpermute_b32 v229, v184, v26
	ds_bpermute_b32 v230, v184, v31
	ds_bpermute_b32 v231, v184, v27
	s_waitcnt lgkmcnt(0)
	v_bfi_b32 v222, v188, v229, v228
	v_bfi_b32 v223, v188, v231, v230
	ds_bpermute_b32 v228, v185, v28
	ds_bpermute_b32 v229, v185, v24
	ds_bpermute_b32 v230, v185, v29
	ds_bpermute_b32 v231, v185, v25
	s_waitcnt lgkmcnt(0)
	v_bfi_b32 v224, v188, v229, v228
	v_bfi_b32 v225, v188, v231, v230
	ds_bpermute_b32 v228, v185, v30
	ds_bpermute_b32 v229, v185, v26
	ds_bpermute_b32 v230, v185, v31
	ds_bpermute_b32 v231, v185, v27
	s_waitcnt lgkmcnt(0)
; #define PG8_BAR __builtin_amdgcn_s_barrier()
; template <class Epi, class Sched, bool ALIGN_EPI = false, bool SP2 = false>
; __device__ __forceinline__ void gemm_phase(PG8_LAS unsigned char* lds, const Gemm g, const Sched& S, const Epi& E) {
;     ...
;         if (!has_next) break;
; #pragma unroll
;         for (int a = 0; a < 2; ++a)
; #pragma unroll
;             for (int b = 0; b < 2; ++b)
; #pragma unroll
;                 for (int m = 0; m < 4; ++m)
; #pragma unroll
;                     for (int n = 0; n < 2; ++n) acc[a][b][m][n] = (f32x4){0.f, 0.f, 0.f, 0.f};
;         cur = nxt; cA = nA; cB = nB; ++ui;
;         if constexpr (ALIGN_EPI) { if (wr == 1) PG8_BAR; }
;     __device__ __forceinline__ void operator()(const pg8::f32x4 (&acc)[2][2][4][2], const pg8::Unit& u, int wr, int wc, int fr, int fq) const {
;     ...
;         for (int ai = 0; ai < 2; ++ai)
; #pragma unroll
;             for (int m = 0; m < 4; ++m) {
;                 float* rowp = base + (size_t)(ai * 128 + wr * 64 + m * 16 + fr) * DM + col0;
; #pragma unroll
;                 for (int bj = 0; bj < 2; ++bj)
; #pragma unroll
;                     for (int n = 0; n < 2; ++n) {
;                         pg8::f32x4* p = (pg8::f32x4*)(rowp + bj * 128 + n * 16);
;                         pg8::f32x4 xv = *p; xv = xv + gv[bj][n] * acc[ai][bj][m][n]; *p = xv;
;                     }
;                 if (m & 1) asm volatile("" ::: "memory");
	v_bfi_b32 v226, v188, v229, v228
	v_bfi_b32 v227, v188, v231, v230
	v_lshl_add_u64 v[178:179], v[168:169], 0, v[162:163]
	ds_bpermute_b32 v180, v184, v178
	ds_bpermute_b32 v181, v184, v179
	ds_bpermute_b32 v198, v185, v178
	ds_bpermute_b32 v199, v185, v179
	s_waitcnt lgkmcnt(0)
	v_lshl_add_u64 v[180:181], v[180:181], 0, v[186:187]
	v_lshl_add_u64 v[198:199], v[198:199], 0, v[186:187]
	global_load_dwordx4 v[28:31], v[180:181], off
	global_load_dwordx4 v[24:27], v[198:199], off
	s_waitcnt vmcnt(8)
	v_pk_fma_f32 v[50:51], v[222:223], v[192:193], v[50:51]
	v_pk_fma_f32 v[48:49], v[220:221], v[190:191], v[48:49]
	v_pk_fma_f32 v[42:43], v[226:227], v[192:193], v[42:43]
	v_pk_fma_f32 v[40:41], v[224:225], v[190:191], v[40:41]
	global_store_dwordx4 v[174:175], v[48:51], off
	global_store_dwordx4 v[176:177], v[40:43], off
	ds_bpermute_b32 v228, v184, v20
	ds_bpermute_b32 v229, v184, v12
	ds_bpermute_b32 v230, v184, v21
	ds_bpermute_b32 v231, v184, v13
	s_waitcnt lgkmcnt(0)
	v_bfi_b32 v220, v188, v229, v228
	v_bfi_b32 v221, v188, v231, v230
	ds_bpermute_b32 v228, v184, v22
	ds_bpermute_b32 v229, v184, v14
	ds_bpermute_b32 v230, v184, v23
	ds_bpermute_b32 v231, v184, v15
	s_waitcnt lgkmcnt(0)
	v_bfi_b32 v222, v188, v229, v228
	v_bfi_b32 v223, v188, v231, v230
	ds_bpermute_b32 v228, v185, v20
	ds_bpermute_b32 v229, v185, v12
	ds_bpermute_b32 v230, v185, v21
	ds_bpermute_b32 v231, v185, v13
	s_waitcnt lgkmcnt(0)
	v_bfi_b32 v224, v188, v229, v228
	v_bfi_b32 v225, v188, v231, v230
	ds_bpermute_b32 v228, v185, v22
	ds_bpermute_b32 v229, v185, v14
	ds_bpermute_b32 v230, v185, v23
	ds_bpermute_b32 v231, v185, v15
	s_waitcnt lgkmcnt(0)
	v_bfi_b32 v226, v188, v229, v228
	v_bfi_b32 v227, v188, v231, v230
	global_load_dwordx4 v[20:23], v[180:181], off offset:512
	global_load_dwordx4 v[12:15], v[198:199], off offset:512
	s_waitcnt vmcnt(8)
	v_pk_fma_f32 v[38:39], v[222:223], v[196:197], v[38:39]
	v_pk_fma_f32 v[36:37], v[220:221], v[194:195], v[36:37]
	v_pk_fma_f32 v[34:35], v[226:227], v[196:197], v[34:35]
	v_pk_fma_f32 v[32:33], v[224:225], v[194:195], v[32:33]
	global_store_dwordx4 v[174:175], v[36:39], off offset:512
	global_store_dwordx4 v[176:177], v[32:35], off offset:512
	ds_bpermute_b32 v228, v184, v16
	ds_bpermute_b32 v229, v184, v8
	ds_bpermute_b32 v230, v184, v17
	ds_bpermute_b32 v231, v184, v9
	s_waitcnt lgkmcnt(0)
	v_bfi_b32 v220, v188, v229, v228
	v_bfi_b32 v221, v188, v231, v230
	ds_bpermute_b32 v228, v184, v18
	ds_bpermute_b32 v229, v184, v10
	ds_bpermute_b32 v230, v184, v19
	ds_bpermute_b32 v231, v184, v11
	s_waitcnt lgkmcnt(0)
	v_bfi_b32 v222, v188, v229, v228
	v_bfi_b32 v223, v188, v231, v230
	ds_bpermute_b32 v228, v185, v16
	ds_bpermute_b32 v229, v185, v8
	ds_bpermute_b32 v230, v185, v17
	ds_bpermute_b32 v231, v185, v9
	s_waitcnt lgkmcnt(0)
	v_bfi_b32 v224, v188, v229, v228
	v_bfi_b32 v225, v188, v231, v230
	ds_bpermute_b32 v228, v185, v18
	ds_bpermute_b32 v229, v185, v10
	ds_bpermute_b32 v230, v185, v19
	ds_bpermute_b32 v231, v185, v11
	s_waitcnt lgkmcnt(0)
	v_bfi_b32 v226, v188, v229, v228
	v_bfi_b32 v227, v188, v231, v230
	s_waitcnt vmcnt(6)
	v_pk_fma_f32 v[30:31], v[222:223], v[192:193], v[30:31]
	v_pk_fma_f32 v[28:29], v[220:221], v[190:191], v[28:29]
	v_pk_fma_f32 v[26:27], v[226:227], v[192:193], v[26:27]
	v_pk_fma_f32 v[24:25], v[224:225], v[190:191], v[24:25]
	global_store_dwordx4 v[180:181], v[28:31], off
	global_store_dwordx4 v[198:199], v[24:27], off
	ds_bpermute_b32 v228, v184, v4
	ds_bpermute_b32 v229, v184, v0
	ds_bpermute_b32 v230, v184, v5
	ds_bpermute_b32 v231, v184, v1
	s_waitcnt lgkmcnt(0)
	v_bfi_b32 v220, v188, v229, v228
	v_bfi_b32 v221, v188, v231, v230
	ds_bpermute_b32 v228, v184, v6
	ds_bpermute_b32 v229, v184, v2
	ds_bpermute_b32 v230, v184, v7
	ds_bpermute_b32 v231, v184, v3
	s_waitcnt lgkmcnt(0)
	v_bfi_b32 v222, v188, v229, v228
	v_bfi_b32 v223, v188, v231, v230
	ds_bpermute_b32 v228, v185, v4
	ds_bpermute_b32 v229, v185, v0
	ds_bpermute_b32 v230, v185, v5
	ds_bpermute_b32 v231, v185, v1
	s_waitcnt lgkmcnt(0)
	v_bfi_b32 v224, v188, v229, v228
	v_bfi_b32 v225, v188, v231, v230
	ds_bpermute_b32 v228, v185, v6
	ds_bpermute_b32 v229, v185, v2
	ds_bpermute_b32 v230, v185, v7
	ds_bpermute_b32 v231, v185, v3
	s_waitcnt lgkmcnt(0)
	v_bfi_b32 v226, v188, v229, v228
	v_bfi_b32 v227, v188, v231, v230
	s_waitcnt vmcnt(4)
	v_pk_fma_f32 v[22:23], v[222:223], v[196:197], v[22:23]
	v_pk_fma_f32 v[20:21], v[220:221], v[194:195], v[20:21]
	v_pk_fma_f32 v[14:15], v[226:227], v[196:197], v[14:15]
	v_pk_fma_f32 v[12:13], v[224:225], v[194:195], v[12:13]
	global_store_dwordx4 v[180:181], v[20:23], off offset:512
	global_store_dwordx4 v[198:199], v[12:15], off offset:512
	s_cbranch_vccnz .LBB0_1111
	s_andn2_b64 vcc, exec, s[0:1]
	s_cbranch_vccnz .LBB0_1110
	s_barrier
	s_branch .LBB0_1110
